# speedup vs baseline: 1.0004x; 1.0004x over previous
; __device__ __forceinline__ void attn_body(const u16* __restrict__ Qb, const u16* __restrict__ Kn, const u16* __restrict__ Kr,
;                                           u16* __restrict__ Ob, char* lds, int tid, const float* __restrict__ gq_, const float* __restrict__ tab_, int qpos0, float negM) {
;     ...
;     const char* Qw = (const char*)Qb + (unsigned)(((wid * 32 + r32) * 1536 + hi * 8) * 2);
;     u32x4 qw[12];
; #pragma unroll
;     for (int d0 = 0; d0 < 12; ++d0) qw[d0] = *reinterpret_cast<const u32x4*>(Qw + d0 * 32);
; __device__ void phase5(const Params& p, char* smem, int wave_s) {
;     ...
;   { const int ln = get_tid(wave_s) & 63;
;     float mq = fmaxf(fmaxf(fabsf(p.g_qk_q[ln]), fabsf(p.g_qk_q[64 + ln])), fabsf(p.g_qk_q[128 + ln]));
;     float mk = fmaxf(fmaxf(fabsf(p.g_qk_k[ln]), fabsf(p.g_qk_k[64 + ln])), fabsf(p.g_qk_k[128 + ln]));
; #pragma unroll
;     for (int o_ = 32; o_ > 0; o_ >>= 1) { mq = fmaxf(mq, __shfl_xor(mq, o_)); mk = fmaxf(mk, __shfl_xor(mk, o_)); }
;     negM = -(13.856406460551018f * 1.4426950408889634f * 1.03f) * mq * mk; }
;   const int xcd = blockIdx.x & 7, slot = blockIdx.x >> 3, per = NBLK >> 3;
;   for (int i = slot; i < NSEQ * NH; i += per) {
.LBB0_715:
	s_or_b64 exec, exec, s[0:1]
	s_barrier
	v_mbcnt_lo_u32_b32 v0, -1, 0
	v_mbcnt_hi_u32_b32 v0, -1, v0
	s_cmpk_gt_u32 s2, 0x9ff
	v_and_b32_e32 v0, 63, v0
	v_lshlrev_b32_e32 v0, 2, v0
	global_load_dword v1, v0, s[52:53]
	global_load_dword v2, v0, s[52:53] offset:256
	global_load_dword v3, v0, s[52:53] offset:512
	global_load_dword v4, v0, s[54:55] offset:512
	global_load_dword v5, v0, s[54:55] offset:256
	global_load_dword v6, v0, s[54:55]
	v_mbcnt_hi_u32_b32 v0, -1, v200
	v_and_b32_e32 v7, 64, v0
	v_xor_b32_e32 v8, 32, v0
	v_add_u32_e32 v7, 64, v7
	v_cmp_lt_i32_e32 vcc, v8, v7
	v_xor_b32_e32 v9, 16, v0
	v_xor_b32_e32 v10, 8, v0
	v_cndmask_b32_e32 v8, v0, v8, vcc
	v_lshlrev_b32_e32 v200, 2, v8
	v_cmp_lt_i32_e32 vcc, v9, v7
	v_xor_b32_e32 v11, 4, v0
	v_xor_b32_e32 v12, 2, v0
	v_xor_b32_e32 v13, 1, v0
	s_mov_b32 s1, 0
	s_waitcnt vmcnt(3)
	v_max3_f32 v1, |v1|, |v2|, |v3|
	ds_bpermute_b32 v3, v200, v1
	s_waitcnt vmcnt(0)
	v_max3_f32 v2, |v6|, |v5|, |v4|
	ds_bpermute_b32 v4, v200, v2
	v_cndmask_b32_e32 v5, v0, v9, vcc
	s_waitcnt lgkmcnt(1)
	v_max_f32_e32 v3, v3, v3
	v_lshlrev_b32_e32 v201, 2, v5
	v_max_f32_e32 v1, v1, v3
	s_waitcnt lgkmcnt(0)
	v_max_f32_e32 v4, v4, v4
	v_max_f32_e32 v2, v2, v4
	ds_bpermute_b32 v3, v201, v1
	ds_bpermute_b32 v4, v201, v2
	v_cmp_lt_i32_e32 vcc, v10, v7
	s_waitcnt lgkmcnt(1)
	v_max_f32_e32 v3, v3, v3
	v_cndmask_b32_e32 v5, v0, v10, vcc
	s_waitcnt lgkmcnt(0)
	v_max_f32_e32 v4, v4, v4
	v_lshlrev_b32_e32 v202, 2, v5
	v_max_f32_e32 v1, v1, v3
	v_max_f32_e32 v2, v2, v4
	ds_bpermute_b32 v3, v202, v1
	ds_bpermute_b32 v4, v202, v2
	v_cmp_lt_i32_e32 vcc, v11, v7
	s_waitcnt lgkmcnt(1)
	v_max_f32_e32 v3, v3, v3
	v_cndmask_b32_e32 v5, v0, v11, vcc
	s_waitcnt lgkmcnt(0)
	v_max_f32_e32 v4, v4, v4
	v_lshlrev_b32_e32 v203, 2, v5
	v_max_f32_e32 v1, v1, v3
	v_max_f32_e32 v2, v2, v4
	ds_bpermute_b32 v3, v203, v1
	ds_bpermute_b32 v4, v203, v2
	v_cmp_lt_i32_e32 vcc, v12, v7
	s_waitcnt lgkmcnt(1)
	v_max_f32_e32 v3, v3, v3
	v_cndmask_b32_e32 v5, v0, v12, vcc
	s_waitcnt lgkmcnt(0)
	v_max_f32_e32 v4, v4, v4
	v_lshlrev_b32_e32 v204, 2, v5
	v_max_f32_e32 v1, v1, v3
	v_max_f32_e32 v2, v2, v4
	ds_bpermute_b32 v3, v204, v1
	ds_bpermute_b32 v4, v204, v2
	v_cmp_lt_i32_e32 vcc, v13, v7
	s_nop 1
	v_cndmask_b32_e32 v0, v0, v13, vcc
	v_lshlrev_b32_e32 v205, 2, v0
	s_waitcnt lgkmcnt(1)
	v_max_f32_e32 v0, v3, v3
	s_waitcnt lgkmcnt(0)
	v_max_f32_e32 v3, v4, v4
	v_max_f32_e32 v0, v1, v0
	v_max_f32_e32 v2, v2, v3
	ds_bpermute_b32 v1, v205, v0
	ds_bpermute_b32 v3, v205, v2
	s_cbranch_scc1 .LBB0_722
	s_and_b32 s0, s2, 7
	s_lshr_b32 s56, s2, 3
	s_mul_i32 s4, s0, 0x180
	s_add_u32 s57, s6, s4
	s_addc_u32 s58, s7, 0
	s_lshl_b32 s4, s0, 8
	s_lshl_b32 s59, s0, 9
	s_add_u32 s61, s50, s59
	s_waitcnt lgkmcnt(1)
	v_max_f32_e32 v1, v1, v1
	v_max_f32_e32 v0, v0, v0
	s_addc_u32 s62, s51, 0
	s_lshl_b32 s63, s0, 7
	s_waitcnt lgkmcnt(0)
	v_max_f32_e32 v3, v3, v3
	v_max_f32_e32 v2, v2, v2
	v_max_f32_e32 v0, v0, v1
	s_add_u32 s65, s44, s63
	v_max_f32_e32 v2, v2, v3
	v_mul_f32_e32 v0, 0xc1a4b8e7, v0
	s_addc_u32 s66, s45, 0
	v_mul_f32_e32 v0, v2, v0
	s_add_u32 s67, s30, s4
	s_mov_b32 s60, s1
	s_mov_b32 s64, s1
	s_addc_u32 s70, s31, 0
	v_mov_b32_e32 v1, v0
	v_mov_b32_e32 v2, v0
	v_mov_b32_e32 v3, v0
	v_mov_b32_e32 v4, v0
	v_mov_b32_e32 v5, v0
	v_mov_b32_e32 v6, v0
	v_mov_b32_e32 v7, v0
	v_mov_b32_e32 v8, v0
	v_mov_b32_e32 v9, v0
	v_mov_b32_e32 v10, v0
	v_mov_b32_e32 v11, v0
	v_mov_b32_e32 v12, v0
	v_mov_b32_e32 v13, v0
	v_mov_b32_e32 v14, v0
	v_mov_b32_e32 v15, v0
	v_mbcnt_lo_u32_b32 v252, -1, 0
	v_mbcnt_hi_u32_b32 v252, -1, v252
	v_lshlrev_b32_e32 v253, 4, v252
	v_cmp_gt_u32_e32 vcc, 48, v252
	s_and_saveexec_b64 s[90:91], vcc
	global_load_dwordx4 v[248:251], v253, s[52:53]
	v_add_u32_e32 v253, 0x1e800, v253
	s_waitcnt vmcnt(0)
	ds_write_b128 v253, v[248:251]
	s_waitcnt lgkmcnt(0)
	s_or_b64 exec, exec, s[90:91]
	s_lshl_b32 s71, s56, 8
	s_movk_i32 s72, 0xc00
	s_movk_i32 s73, 0xc0
	s_movk_i32 s74, 0xf0
	s_movk_i32 s75, 0x70
	v_mov_b32_e32 v177, 0
	s_mov_b64 s[4:5], 0x100
	s_movk_i32 s76, 0xffe0
	s_mov_b64 s[10:11], 0x40000
	s_mov_b64 s[12:13], 0x40040
	s_mov_b32 s77, 0x800000
	s_mov_b32 s78, 0x40000
	s_mov_b64 s[14:15], 0x10000
	s_mov_b64 s[16:17], 0x16a80000
	s_mov_b64 s[18:19], 0x2aa20000
	s_mov_b64 s[20:21], 0x16a80100
	s_mov_b64 s[22:23], 0x16ac0000
	s_mov_b64 s[40:41], 0x2aa30000
	s_mov_b64 s[42:43], 0x16ac0100
	s_mov_b64 s[44:45], 0x20000
	s_mov_b64 s[46:47], 0x80000
	s_mul_i32 s93, s56, 0xc0000
	s_lshl_b32 s92, s56, 8
	s_mul_hi_u32 s92, s92, 0xc00
	s_add_u32 s90, s57, s93
	s_addc_u32 s91, s58, s92
	v_mbcnt_lo_u32_b32 v252, -1, 0
	v_mbcnt_hi_u32_b32 v252, -1, v252
	v_or_b32_e32 v253, s3, v252
	v_ashrrev_i32_e32 v253, 1, v253
	v_bfi_b32 v253, s76, v253, v252
	v_mul_lo_u32 v253, v253, s72
	v_bfe_u32 v252, v252, 5, 1
	v_lshl_or_b32 v252, v252, 4, v253
	global_load_dwordx4 v[128:131], v252, s[90:91]
	global_load_dwordx4 v[132:135], v252, s[90:91] offset:32
	global_load_dwordx4 v[136:139], v252, s[90:91] offset:64
	global_load_dwordx4 v[140:143], v252, s[90:91] offset:96
	global_load_dwordx4 v[144:147], v252, s[90:91] offset:128
	global_load_dwordx4 v[148:151], v252, s[90:91] offset:160
	global_load_dwordx4 v[152:155], v252, s[90:91] offset:192
	global_load_dwordx4 v[156:159], v252, s[90:91] offset:224
	global_load_dwordx4 v[160:163], v252, s[90:91] offset:256
	global_load_dwordx4 v[164:167], v252, s[90:91] offset:288
	global_load_dwordx4 v[168:171], v252, s[90:91] offset:320
	global_load_dwordx4 v[172:175], v252, s[90:91] offset:352
	s_branch .LBB0_718
; __device__ __forceinline__ u16 f2bf(float x) { return (u16)(cvtpk(x, x) & 0xffffu); }
; __device__ __forceinline__ int crow(int r, int hi) { return (r & 3) + 8 * (r >> 2) + 4 * hi; }
; __device__ __forceinline__ void attn_body(const u16* __restrict__ Qb, const u16* __restrict__ Kn, const u16* __restrict__ Kr,
;                                           u16* __restrict__ Ob, char* lds, int tid, const float* __restrict__ gq_, const float* __restrict__ tab_, int qpos0, float negM) {
;     ...
;     const char* Qw = (const char*)Qb + (unsigned)(((wid * 32 + r32) * 1536 + hi * 8) * 2);
;     u32x4 qw[12];
; #pragma unroll
;     for (int d0 = 0; d0 < 12; ++d0) qw[d0] = *reinterpret_cast<const u32x4*>(Qw + d0 * 32);
;     ...
;   if (hi == 0) li_l[r32] = l_reg; asm volatile("s_waitcnt lgkmcnt(0)" ::: "memory");
;   float rli[16];
; #pragma unroll
;   for (int r = 0; r < 16; ++r) rli[r] = __builtin_amdgcn_rcpf(li_l[crow(r, hi)]);
;   const unsigned ow = (unsigned)((wid * 32 + 4 * hi) * 1024 + r32);
; #pragma unroll
;   for (int r = 0; r < 16; ++r) {
; #pragma unroll
;     for (int d0 = 0; d0 < 4; ++d0) Ob[ow + (unsigned)(((r & 3) + 8 * (r >> 2)) * 1024 + d0 * 32)] = f2bf(o[d0][r] * rli[r]); }
.LBB0_717:
	s_or_b64 exec, exec, s[48:49]
	s_add_i32 s92, s56, 32
	s_mul_i32 s93, s92, 0xc0000
	s_lshl_b32 s92, s92, 8
	s_mul_hi_u32 s92, s92, 0xc00
	s_add_u32 s90, s57, s93
	s_addc_u32 s91, s58, s92
	v_mbcnt_lo_u32_b32 v252, -1, 0
	v_mbcnt_hi_u32_b32 v252, -1, v252
	v_or_b32_e32 v253, s3, v252
	v_ashrrev_i32_e32 v253, 1, v253
	v_bfi_b32 v253, s76, v253, v252
	v_mul_lo_u32 v253, v253, s72
	v_bfe_u32 v252, v252, 5, 1
	v_lshl_or_b32 v252, v252, 4, v253
	global_load_dwordx4 v[128:131], v252, s[90:91]
	global_load_dwordx4 v[132:135], v252, s[90:91] offset:32
	global_load_dwordx4 v[136:139], v252, s[90:91] offset:64
	global_load_dwordx4 v[140:143], v252, s[90:91] offset:96
	global_load_dwordx4 v[144:147], v252, s[90:91] offset:128
	global_load_dwordx4 v[148:151], v252, s[90:91] offset:160
	global_load_dwordx4 v[152:155], v252, s[90:91] offset:192
	global_load_dwordx4 v[156:159], v252, s[90:91] offset:224
	global_load_dwordx4 v[160:163], v252, s[90:91] offset:256
	global_load_dwordx4 v[164:167], v252, s[90:91] offset:288
	global_load_dwordx4 v[168:171], v252, s[90:91] offset:320
	global_load_dwordx4 v[172:175], v252, s[90:91] offset:352
	s_waitcnt lgkmcnt(0)
	v_lshl_add_u32 v88, v207, 4, v178
	ds_read_b128 v[80:83], v88
	ds_read_b128 v[84:87], v88 offset:32
	s_lshl_b64 s[48:49], s[0:1], 11
	s_add_u32 s48, s67, s48
	s_addc_u32 s49, s70, s49
	s_waitcnt lgkmcnt(0)
	v_rcp_f32_e32 v89, v80
	v_rcp_f32_e32 v90, v81
	v_rcp_f32_e32 v91, v82
	v_rcp_f32_e32 v92, v83
	ds_read_b128 v[80:83], v88 offset:64
	v_rcp_f32_e32 v93, v84
	v_rcp_f32_e32 v94, v85
	v_rcp_f32_e32 v95, v86
	v_rcp_f32_e32 v96, v87
	ds_read_b128 v[84:87], v88 offset:96
	s_waitcnt lgkmcnt(0)
	v_rcp_f32_e32 v88, v80
	v_rcp_f32_e32 v97, v81
	v_lshlrev_b32_e32 v80, 12, v207
	v_lshlrev_b32_e32 v81, 10, v208
	v_or3_b32 v176, v81, v80, v206
	v_mul_f32_e32 v16, v16, v89
	v_lshl_add_u64 v[80:81], v[176:177], 1, s[48:49]
	s_nop 0
	v_cvt_pk_bf16_f32 v16, v16, v16
	global_store_short v[80:81], v16, off offset:192
	v_mul_f32_e32 v16, v65, v90
	s_nop 0
	v_cvt_pk_bf16_f32 v16, v16, v16
	global_store_short v[80:81], v16, off offset:2048
	v_mul_f32_e32 v16, v49, v90
	s_nop 0
	v_cvt_pk_bf16_f32 v16, v16, v16
	global_store_short v[80:81], v16, off offset:2112
	v_mul_f32_e32 v16, v33, v90
	s_nop 0
	v_cvt_pk_bf16_f32 v16, v16, v16
	v_mul_f32_e32 v32, v32, v89
	global_store_short v[80:81], v16, off offset:2176
	v_mul_f32_e32 v16, v17, v90
	s_nop 0
	v_cvt_pk_bf16_f32 v32, v32, v32
	s_nop 0
	v_cvt_pk_bf16_f32 v16, v16, v16
	v_mul_f32_e32 v17, v66, v91
	global_store_short v[80:81], v32, off offset:128
	global_store_short v[80:81], v16, off offset:2240
	v_or_b32_e32 v16, 0x800, v176
	s_nop 0
	v_cvt_pk_bf16_f32 v32, v17, v17
	v_mov_b32_e32 v17, v177
	v_lshl_add_u64 v[16:17], v[16:17], 1, s[48:49]
	global_store_short v[16:17], v32, off
	v_mul_f32_e32 v16, v50, v91
	s_nop 0
	v_cvt_pk_bf16_f32 v32, v16, v16
	v_or_b32_e32 v16, 0x820, v176
	v_mov_b32_e32 v17, v177
	v_lshl_add_u64 v[16:17], v[16:17], 1, s[48:49]
	global_store_short v[16:17], v32, off
	v_mul_f32_e32 v16, v34, v91
	s_nop 0
	v_cvt_pk_bf16_f32 v32, v16, v16
	v_or_b32_e32 v16, 0x840, v176
	v_mov_b32_e32 v17, v177
	v_lshl_add_u64 v[16:17], v[16:17], 1, s[48:49]
	global_store_short v[16:17], v32, off
	v_mul_f32_e32 v16, v18, v91
	s_nop 0
	v_cvt_pk_bf16_f32 v18, v16, v16
	v_or_b32_e32 v16, 0x860, v176
	v_mov_b32_e32 v17, v177
	v_lshl_add_u64 v[16:17], v[16:17], 1, s[48:49]
	global_store_short v[16:17], v18, off
	v_mul_f32_e32 v17, v67, v92
	v_or_b32_e32 v16, 0xc00, v176
	s_nop 0
	v_cvt_pk_bf16_f32 v18, v17, v17
	v_mov_b32_e32 v17, v177
	v_lshl_add_u64 v[16:17], v[16:17], 1, s[48:49]
	global_store_short v[16:17], v18, off
	v_mul_f32_e32 v16, v51, v92
	s_nop 0
	v_cvt_pk_bf16_f32 v18, v16, v16
	v_or_b32_e32 v16, 0xc20, v176
	v_mov_b32_e32 v17, v177
	v_lshl_add_u64 v[16:17], v[16:17], 1, s[48:49]
	global_store_short v[16:17], v18, off
	v_mul_f32_e32 v16, v35, v92
	s_nop 0
	v_cvt_pk_bf16_f32 v18, v16, v16
	v_or_b32_e32 v16, 0xc40, v176
	v_mov_b32_e32 v17, v177
	v_lshl_add_u64 v[16:17], v[16:17], 1, s[48:49]
	global_store_short v[16:17], v18, off
	v_mul_f32_e32 v16, v19, v92
	s_nop 0
	v_cvt_pk_bf16_f32 v18, v16, v16
	v_or_b32_e32 v16, 0xc60, v176
	v_mov_b32_e32 v17, v177
	v_lshl_add_u64 v[16:17], v[16:17], 1, s[48:49]
	global_store_short v[16:17], v18, off
	v_mul_f32_e32 v17, v68, v93
	v_or_b32_e32 v16, 0x2000, v176
	s_nop 0
	v_cvt_pk_bf16_f32 v18, v17, v17
	v_mov_b32_e32 v17, v177
	v_lshl_add_u64 v[16:17], v[16:17], 1, s[48:49]
	global_store_short v[16:17], v18, off
	v_mul_f32_e32 v16, v52, v93
	s_nop 0
	v_cvt_pk_bf16_f32 v18, v16, v16
	v_or_b32_e32 v16, 0x2020, v176
	v_mov_b32_e32 v17, v177
	v_lshl_add_u64 v[16:17], v[16:17], 1, s[48:49]
	global_store_short v[16:17], v18, off
	v_mul_f32_e32 v16, v36, v93
	s_nop 0
	v_cvt_pk_bf16_f32 v18, v16, v16
	v_or_b32_e32 v16, 0x2040, v176
	v_mov_b32_e32 v17, v177
	v_lshl_add_u64 v[16:17], v[16:17], 1, s[48:49]
	global_store_short v[16:17], v18, off
	v_mul_f32_e32 v16, v20, v93
	s_nop 0
	v_cvt_pk_bf16_f32 v18, v16, v16
	v_or_b32_e32 v16, 0x2060, v176
	v_mov_b32_e32 v17, v177
	v_lshl_add_u64 v[16:17], v[16:17], 1, s[48:49]
	global_store_short v[16:17], v18, off
	v_mul_f32_e32 v17, v69, v94
	v_or_b32_e32 v16, 0x2400, v176
	s_nop 0
	v_cvt_pk_bf16_f32 v18, v17, v17
	v_mov_b32_e32 v17, v177
	v_lshl_add_u64 v[16:17], v[16:17], 1, s[48:49]
	global_store_short v[16:17], v18, off
	v_mul_f32_e32 v16, v53, v94
	s_nop 0
	v_cvt_pk_bf16_f32 v18, v16, v16
	v_or_b32_e32 v16, 0x2420, v176
	v_mov_b32_e32 v17, v177
	v_lshl_add_u64 v[16:17], v[16:17], 1, s[48:49]
	global_store_short v[16:17], v18, off
	v_mul_f32_e32 v16, v37, v94
	s_nop 0
; __device__ __forceinline__ u16 f2bf(float x) { return (u16)(cvtpk(x, x) & 0xffffu); }
; __device__ __forceinline__ int crow(int r, int hi) { return (r & 3) + 8 * (r >> 2) + 4 * hi; }
; __device__ __forceinline__ void attn_body(const u16* __restrict__ Qb, const u16* __restrict__ Kn, const u16* __restrict__ Kr,
;                                           u16* __restrict__ Ob, char* lds, int tid, const float* __restrict__ gq_, const float* __restrict__ tab_, int qpos0, float negM) {
;     ...
;   for (int r = 0; r < 16; ++r) rli[r] = __builtin_amdgcn_rcpf(li_l[crow(r, hi)]);
;   const unsigned ow = (unsigned)((wid * 32 + 4 * hi) * 1024 + r32);
; #pragma unroll
;   for (int r = 0; r < 16; ++r) {
; #pragma unroll
;     for (int d0 = 0; d0 < 4; ++d0) Ob[ow + (unsigned)(((r & 3) + 8 * (r >> 2)) * 1024 + d0 * 32)] = f2bf(o[d0][r] * rli[r]); }
	v_cvt_pk_bf16_f32 v18, v16, v16
	v_or_b32_e32 v16, 0x2440, v176
	v_mov_b32_e32 v17, v177
	v_lshl_add_u64 v[16:17], v[16:17], 1, s[48:49]
	global_store_short v[16:17], v18, off
	v_mul_f32_e32 v16, v21, v94
	s_nop 0
	v_cvt_pk_bf16_f32 v18, v16, v16
	v_or_b32_e32 v16, 0x2460, v176
	v_mov_b32_e32 v17, v177
	v_lshl_add_u64 v[16:17], v[16:17], 1, s[48:49]
	global_store_short v[16:17], v18, off
	v_mul_f32_e32 v17, v70, v95
	v_or_b32_e32 v16, 0x2800, v176
	s_nop 0
	v_cvt_pk_bf16_f32 v18, v17, v17
	v_mov_b32_e32 v17, v177
	v_lshl_add_u64 v[16:17], v[16:17], 1, s[48:49]
	global_store_short v[16:17], v18, off
	v_mul_f32_e32 v16, v54, v95
	s_nop 0
	v_cvt_pk_bf16_f32 v18, v16, v16
	v_or_b32_e32 v16, 0x2820, v176
	v_mov_b32_e32 v17, v177
	v_lshl_add_u64 v[16:17], v[16:17], 1, s[48:49]
	global_store_short v[16:17], v18, off
	v_mul_f32_e32 v16, v38, v95
	s_nop 0
	v_cvt_pk_bf16_f32 v18, v16, v16
	v_or_b32_e32 v16, 0x2840, v176
	v_mov_b32_e32 v17, v177
	v_lshl_add_u64 v[16:17], v[16:17], 1, s[48:49]
	global_store_short v[16:17], v18, off
	v_mul_f32_e32 v16, v22, v95
	s_nop 0
	v_cvt_pk_bf16_f32 v18, v16, v16
	v_or_b32_e32 v16, 0x2860, v176
	v_mov_b32_e32 v17, v177
	v_lshl_add_u64 v[16:17], v[16:17], 1, s[48:49]
	global_store_short v[16:17], v18, off
	v_mul_f32_e32 v17, v71, v96
	v_or_b32_e32 v16, 0x2c00, v176
	s_nop 0
	v_cvt_pk_bf16_f32 v18, v17, v17
	v_mov_b32_e32 v17, v177
	v_lshl_add_u64 v[16:17], v[16:17], 1, s[48:49]
	global_store_short v[16:17], v18, off
	v_mul_f32_e32 v16, v55, v96
	s_nop 0
	v_cvt_pk_bf16_f32 v18, v16, v16
	v_or_b32_e32 v16, 0x2c20, v176
	v_mov_b32_e32 v17, v177
	v_lshl_add_u64 v[16:17], v[16:17], 1, s[48:49]
	global_store_short v[16:17], v18, off
	v_mul_f32_e32 v16, v39, v96
	s_nop 0
	v_cvt_pk_bf16_f32 v18, v16, v16
	v_or_b32_e32 v16, 0x2c40, v176
	v_mov_b32_e32 v17, v177
	v_lshl_add_u64 v[16:17], v[16:17], 1, s[48:49]
	global_store_short v[16:17], v18, off
	v_mul_f32_e32 v16, v23, v96
	s_nop 0
	v_cvt_pk_bf16_f32 v18, v16, v16
	v_or_b32_e32 v16, 0x2c60, v176
	v_mov_b32_e32 v17, v177
	v_lshl_add_u64 v[16:17], v[16:17], 1, s[48:49]
	global_store_short v[16:17], v18, off
	v_mul_f32_e32 v17, v72, v88
	v_or_b32_e32 v16, 0x4000, v176
	s_nop 0
	v_cvt_pk_bf16_f32 v18, v17, v17
	v_mov_b32_e32 v17, v177
	v_lshl_add_u64 v[16:17], v[16:17], 1, s[48:49]
	global_store_short v[16:17], v18, off
	v_mul_f32_e32 v16, v56, v88
	s_nop 0
	v_cvt_pk_bf16_f32 v18, v16, v16
	v_or_b32_e32 v16, 0x4020, v176
	v_mov_b32_e32 v17, v177
	v_lshl_add_u64 v[16:17], v[16:17], 1, s[48:49]
	global_store_short v[16:17], v18, off
	v_mul_f32_e32 v16, v40, v88
	s_nop 0
	v_cvt_pk_bf16_f32 v18, v16, v16
	v_or_b32_e32 v16, 0x4040, v176
	v_mov_b32_e32 v17, v177
	v_lshl_add_u64 v[16:17], v[16:17], 1, s[48:49]
	global_store_short v[16:17], v18, off
	v_mul_f32_e32 v16, v24, v88
	s_nop 0
	v_cvt_pk_bf16_f32 v18, v16, v16
	v_or_b32_e32 v16, 0x4060, v176
	v_mov_b32_e32 v17, v177
	v_lshl_add_u64 v[16:17], v[16:17], 1, s[48:49]
	global_store_short v[16:17], v18, off
	v_mul_f32_e32 v17, v73, v97
	v_or_b32_e32 v16, 0x4400, v176
	s_nop 0
	v_cvt_pk_bf16_f32 v18, v17, v17
	v_mov_b32_e32 v17, v177
	v_lshl_add_u64 v[16:17], v[16:17], 1, s[48:49]
	global_store_short v[16:17], v18, off
	v_mul_f32_e32 v16, v57, v97
	s_nop 0
	v_cvt_pk_bf16_f32 v18, v16, v16
	v_or_b32_e32 v16, 0x4420, v176
	v_mov_b32_e32 v17, v177
	v_lshl_add_u64 v[16:17], v[16:17], 1, s[48:49]
	global_store_short v[16:17], v18, off
	v_mul_f32_e32 v16, v41, v97
	s_nop 0
	v_cvt_pk_bf16_f32 v18, v16, v16
	v_or_b32_e32 v16, 0x4440, v176
	v_mov_b32_e32 v17, v177
	v_rcp_f32_e32 v82, v82
	v_lshl_add_u64 v[16:17], v[16:17], 1, s[48:49]
	global_store_short v[16:17], v18, off
	v_mul_f32_e32 v16, v25, v97
	s_nop 0
	v_cvt_pk_bf16_f32 v18, v16, v16
	v_or_b32_e32 v16, 0x4460, v176
	v_mov_b32_e32 v17, v177
	v_lshl_add_u64 v[16:17], v[16:17], 1, s[48:49]
	global_store_short v[16:17], v18, off
	v_mul_f32_e32 v17, v74, v82
	v_or_b32_e32 v16, 0x4800, v176
	s_nop 0
	v_cvt_pk_bf16_f32 v18, v17, v17
	v_mov_b32_e32 v17, v177
	v_lshl_add_u64 v[16:17], v[16:17], 1, s[48:49]
	global_store_short v[16:17], v18, off
	v_mul_f32_e32 v16, v58, v82
	s_nop 0
	v_cvt_pk_bf16_f32 v18, v16, v16
	v_or_b32_e32 v16, 0x4820, v176
	v_mov_b32_e32 v17, v177
	v_lshl_add_u64 v[16:17], v[16:17], 1, s[48:49]
	global_store_short v[16:17], v18, off
	v_mul_f32_e32 v16, v42, v82
	s_nop 0
	v_cvt_pk_bf16_f32 v18, v16, v16
	v_or_b32_e32 v16, 0x4840, v176
	v_mov_b32_e32 v17, v177
	v_rcp_f32_e32 v83, v83
	v_lshl_add_u64 v[16:17], v[16:17], 1, s[48:49]
	global_store_short v[16:17], v18, off
	v_mul_f32_e32 v16, v26, v82
	s_nop 0
	v_cvt_pk_bf16_f32 v18, v16, v16
	v_or_b32_e32 v16, 0x4860, v176
	v_mov_b32_e32 v17, v177
	v_lshl_add_u64 v[16:17], v[16:17], 1, s[48:49]
	global_store_short v[16:17], v18, off
	v_mul_f32_e32 v17, v75, v83
	v_or_b32_e32 v16, 0x4c00, v176
	s_nop 0
	v_cvt_pk_bf16_f32 v18, v17, v17
	v_mov_b32_e32 v17, v177
	v_lshl_add_u64 v[16:17], v[16:17], 1, s[48:49]
	global_store_short v[16:17], v18, off
	v_mul_f32_e32 v16, v59, v83
	s_nop 0
	v_cvt_pk_bf16_f32 v18, v16, v16
	v_or_b32_e32 v16, 0x4c20, v176
	v_mov_b32_e32 v17, v177
	v_lshl_add_u64 v[16:17], v[16:17], 1, s[48:49]
	global_store_short v[16:17], v18, off
	v_mul_f32_e32 v16, v43, v83
	s_nop 0
	v_cvt_pk_bf16_f32 v18, v16, v16
	v_or_b32_e32 v16, 0x4c40, v176
	v_mov_b32_e32 v17, v177
	v_rcp_f32_e32 v84, v84
	v_lshl_add_u64 v[16:17], v[16:17], 1, s[48:49]
	global_store_short v[16:17], v18, off
	v_mul_f32_e32 v16, v27, v83
	s_nop 0
	v_cvt_pk_bf16_f32 v18, v16, v16
	v_or_b32_e32 v16, 0x4c60, v176
	v_mov_b32_e32 v17, v177
	v_lshl_add_u64 v[16:17], v[16:17], 1, s[48:49]
	global_store_short v[16:17], v18, off
	v_mul_f32_e32 v17, v76, v84
; __device__ __forceinline__ u16 f2bf(float x) { return (u16)(cvtpk(x, x) & 0xffffu); }
; __device__ __forceinline__ int crow(int r, int hi) { return (r & 3) + 8 * (r >> 2) + 4 * hi; }
; __device__ __forceinline__ void attn_body(const u16* __restrict__ Qb, const u16* __restrict__ Kn, const u16* __restrict__ Kr,
;                                           u16* __restrict__ Ob, char* lds, int tid, const float* __restrict__ gq_, const float* __restrict__ tab_, int qpos0, float negM) {
;     ...
;   for (int r = 0; r < 16; ++r) rli[r] = __builtin_amdgcn_rcpf(li_l[crow(r, hi)]);
;   const unsigned ow = (unsigned)((wid * 32 + 4 * hi) * 1024 + r32);
; #pragma unroll
;   for (int r = 0; r < 16; ++r) {
; #pragma unroll
;     for (int d0 = 0; d0 < 4; ++d0) Ob[ow + (unsigned)(((r & 3) + 8 * (r >> 2)) * 1024 + d0 * 32)] = f2bf(o[d0][r] * rli[r]); }
; __device__ void phase5(const Params& p, char* smem, int wave_s) {
;     ...
;   for (int i = slot; i < NSEQ * NH; i += per) {
;     const int tid = get_tid(wave_s);
;     const int pair = xcd + 8 * (i >> 3), qb = i & 7, seq = pair >> 3, h = pair & 7;
;     const size_t tok0 = (size_t)seq * SEQ, qtok = tok0 + (size_t)qb * 256;
;     __syncthreads();
	v_or_b32_e32 v16, 0x6000, v176
	s_nop 0
	v_cvt_pk_bf16_f32 v18, v17, v17
	v_mov_b32_e32 v17, v177
	v_lshl_add_u64 v[16:17], v[16:17], 1, s[48:49]
	global_store_short v[16:17], v18, off
	v_mul_f32_e32 v16, v60, v84
	s_nop 0
	v_cvt_pk_bf16_f32 v18, v16, v16
	v_or_b32_e32 v16, 0x6020, v176
	v_mov_b32_e32 v17, v177
	v_lshl_add_u64 v[16:17], v[16:17], 1, s[48:49]
	global_store_short v[16:17], v18, off
	v_mul_f32_e32 v16, v44, v84
	s_nop 0
	v_cvt_pk_bf16_f32 v18, v16, v16
	v_or_b32_e32 v16, 0x6040, v176
	v_mov_b32_e32 v17, v177
	v_rcp_f32_e32 v85, v85
	v_lshl_add_u64 v[16:17], v[16:17], 1, s[48:49]
	global_store_short v[16:17], v18, off
	v_mul_f32_e32 v16, v28, v84
	s_nop 0
	v_cvt_pk_bf16_f32 v18, v16, v16
	v_or_b32_e32 v16, 0x6060, v176
	v_mov_b32_e32 v17, v177
	v_lshl_add_u64 v[16:17], v[16:17], 1, s[48:49]
	global_store_short v[16:17], v18, off
	v_mul_f32_e32 v17, v77, v85
	v_or_b32_e32 v16, 0x6400, v176
	s_nop 0
	v_cvt_pk_bf16_f32 v18, v17, v17
	v_mov_b32_e32 v17, v177
	v_lshl_add_u64 v[16:17], v[16:17], 1, s[48:49]
	global_store_short v[16:17], v18, off
	v_mul_f32_e32 v16, v61, v85
	s_nop 0
	v_cvt_pk_bf16_f32 v18, v16, v16
	v_or_b32_e32 v16, 0x6420, v176
	v_mov_b32_e32 v17, v177
	v_lshl_add_u64 v[16:17], v[16:17], 1, s[48:49]
	global_store_short v[16:17], v18, off
	v_mul_f32_e32 v16, v45, v85
	s_nop 0
	v_cvt_pk_bf16_f32 v18, v16, v16
	v_or_b32_e32 v16, 0x6440, v176
	v_mov_b32_e32 v17, v177
	v_rcp_f32_e32 v86, v86
	v_lshl_add_u64 v[16:17], v[16:17], 1, s[48:49]
	global_store_short v[16:17], v18, off
	v_mul_f32_e32 v16, v29, v85
	s_nop 0
	v_cvt_pk_bf16_f32 v18, v16, v16
	v_or_b32_e32 v16, 0x6460, v176
	v_mov_b32_e32 v17, v177
	v_lshl_add_u64 v[16:17], v[16:17], 1, s[48:49]
	global_store_short v[16:17], v18, off
	v_mul_f32_e32 v17, v78, v86
	v_or_b32_e32 v16, 0x6800, v176
	s_nop 0
	v_cvt_pk_bf16_f32 v18, v17, v17
	v_mov_b32_e32 v17, v177
	v_lshl_add_u64 v[16:17], v[16:17], 1, s[48:49]
	global_store_short v[16:17], v18, off
	v_mul_f32_e32 v16, v62, v86
	s_nop 0
	v_cvt_pk_bf16_f32 v18, v16, v16
	v_or_b32_e32 v16, 0x6820, v176
	v_mov_b32_e32 v17, v177
	v_lshl_add_u64 v[16:17], v[16:17], 1, s[48:49]
	global_store_short v[16:17], v18, off
	v_mul_f32_e32 v16, v46, v86
	s_nop 0
	v_cvt_pk_bf16_f32 v18, v16, v16
	v_or_b32_e32 v16, 0x6840, v176
	v_mov_b32_e32 v17, v177
	v_rcp_f32_e32 v87, v87
	v_lshl_add_u64 v[16:17], v[16:17], 1, s[48:49]
	global_store_short v[16:17], v18, off
	v_mul_f32_e32 v16, v30, v86
	s_nop 0
	v_cvt_pk_bf16_f32 v18, v16, v16
	v_or_b32_e32 v16, 0x6860, v176
	v_mov_b32_e32 v17, v177
	v_lshl_add_u64 v[16:17], v[16:17], 1, s[48:49]
	global_store_short v[16:17], v18, off
	v_mul_f32_e32 v17, v79, v87
	v_or_b32_e32 v16, 0x6c00, v176
	s_nop 0
	v_cvt_pk_bf16_f32 v18, v17, v17
	v_mov_b32_e32 v17, v177
	v_lshl_add_u64 v[16:17], v[16:17], 1, s[48:49]
	global_store_short v[16:17], v18, off
	v_mul_f32_e32 v16, v63, v87
	s_nop 0
	v_cvt_pk_bf16_f32 v18, v16, v16
	v_or_b32_e32 v16, 0x6c20, v176
	v_mov_b32_e32 v17, v177
	v_lshl_add_u64 v[16:17], v[16:17], 1, s[48:49]
	global_store_short v[16:17], v18, off
	v_mul_f32_e32 v16, v47, v87
	s_nop 0
	v_cvt_pk_bf16_f32 v18, v16, v16
	v_or_b32_e32 v16, 0x6c40, v176
	v_mov_b32_e32 v17, v177
	v_lshl_add_u64 v[16:17], v[16:17], 1, s[48:49]
	global_store_short v[16:17], v18, off
	v_mul_f32_e32 v16, v31, v87
	v_or_b32_e32 v176, 0x6c60, v176
	s_add_i32 s0, s56, 32
	s_addk_i32 s71, 0x2000
	v_mul_f32_e32 v64, v64, v89
	v_mul_f32_e32 v48, v48, v89
	s_nop 0
	v_cvt_pk_bf16_f32 v18, v16, v16
	v_lshl_add_u64 v[16:17], v[176:177], 1, s[48:49]
	s_cmpk_lt_u32 s56, 0x120
	s_mov_b32 s56, s0
	s_nop 0
	v_cvt_pk_bf16_f32 v64, v64, v64
	global_store_short v[80:81], v64, off
	s_nop 0
	v_cvt_pk_bf16_f32 v48, v48, v48
	global_store_short v[80:81], v48, off offset:64
	global_store_short v[16:17], v18, off
	s_cbranch_scc0 .LBB0_722
.LBB0_718:
	s_lshl_b32 s87, s3, 4
	s_lshl_b32 s0, s71, 10
	s_and_b32 s80, s0, 0x7e00000
	s_lshl_b32 s0, s71, 12
	v_mbcnt_lo_u32_b32 v96, -1, 0
	v_mbcnt_hi_u32_b32 v96, -1, v96
	s_and_b32 s79, s0, 0x1f800000
	v_or_b32_e32 v210, s3, v96
	s_lshl_b32 s0, s56, 8
	v_ashrrev_i32_e32 v20, 1, v210
	s_and_b32 s54, s0, 0x1f800
	s_mul_i32 s48, s56, 0xc0000
	v_bfi_b32 v66, s76, v20, v96
	s_mul_hi_u32 s49, s0, 0xc00
	s_add_u32 s50, s57, s48
	v_bfe_u32 v207, v96, 5, 1
	v_mul_lo_u32 v21, v66, s72
	s_addc_u32 s51, s58, s49
	v_lshl_or_b32 v67, v207, 4, v21
	s_barrier
; __device__ __forceinline__ float bflo(unsigned w) { return __uint_as_float(w << 16); }
; __device__ __forceinline__ float bfhi(unsigned w) { return __uint_as_float(w & 0xffff0000u); }
; #define AISSUE(k0, soff) do { const char* kb_ = (const char*)Kn + (size_t)(k0) * 4096; const char* rb_ = (const char*)Kr + (size_t)(k0) * 1024; \
;     char* st_ = lds + (soff) + tid * 16; \
;     GLDS(kb_ + vkn0, st_ + KOFF); GLDS(kb_ + vkn1, st_ + KOFF + 8192); GLDS(rb_ + vkr, st_ + KOFF + KROPE_OFF); \
;     GLDS(kb_ + vv0, st_); GLDS(kb_ + vv1, st_ + 8192); } while (0)
; __device__ __forceinline__ void attn_body(const u16* __restrict__ Qb, const u16* __restrict__ Kn, const u16* __restrict__ Kr,
;                                           u16* __restrict__ Ob, char* lds, int tid, const float* __restrict__ gq_, const float* __restrict__ tab_, int qpos0, float negM) {
;     ...
;   { int sl = tid;        int row = sl >> 4, c = (sl & 15) ^ (row & 15);        vkn0 = (unsigned)(row * 4096 + c * 16);
;     sl = tid + 512;      row = sl >> 4;     c = (sl & 15) ^ (row & 15);        vkn1 = (unsigned)(row * 4096 + c * 16);
;     row = tid >> 3;      c = (tid & 7) ^ ((row >> 1) & 7);                     vkr  = (unsigned)(row * 1024 + c * 16);
; #pragma unroll
;     for (int i = 0; i < 2; ++i) { const int o = (tid + i * 512) * 16, sub = o >> 9, within = o & 511;
;       const int kk = (sub >> 2) * 8 + (within >> 6), cc = (sub & 3) * 32 + ((within & 63) >> 1);
;       const int k = (kk & ~0xC) | ((kk & 4) << 1) | ((kk & 8) >> 1);
;       const unsigned v = (unsigned)(k * 4096 + cc * 2 + 256);
;       if (i == 0) vv0 = v; else vv1 = v; } }
;   constexpr int STG = 40960, KOFF = 16384;
;     ...
;   AISSUE(0, 0);
;   {
;     const char* Qw = (const char*)Qb + (unsigned)(((wid * 32 + r32) * 1536 + hi * 8) * 2);
;     u32x4 qw[12];
; #pragma unroll
;     for (int d0 = 0; d0 < 12; ++d0) qw[d0] = *reinterpret_cast<const u32x4*>(Qw + d0 * 32);
;     float ss = 0.f;
; #pragma unroll
;     for (int d0 = 0; d0 < 12; ++d0)
; #pragma unroll
;       for (int e = 0; e < 4; ++e) { const float a = bflo(qw[d0][e]), b = bfhi(qw[d0][e]); ss += a * a + b * b; }
	v_lshlrev_b32_e32 v211, 4, v210
	v_bfe_u32 v23, v210, 2, 2
	v_lshrrev_b32_e32 v28, 1, v210
	v_and_or_b32 v23, v28, 8, v23
	v_lshlrev_b32_e32 v28, 1, v210
	v_and_b32_e32 v29, 48, v211
	v_and_or_b32 v38, v28, s73, v29
	v_bfe_i32 v28, v210, 4, 24
	v_and_b32_e32 v29, 0xffff0, v28
	v_lshrrev_b32_e32 v28, 1, v28
	v_and_b32_e32 v28, 4, v28
	v_or3_b32 v28, v29, v28, v23
	v_lshlrev_b32_e32 v36, 12, v28
	v_add_u32_e32 v50, 0x2000, v211
	v_ashrrev_i32_e32 v33, 8, v50
	v_ashrrev_i32_e32 v16, 4, v210
	v_add_u32_e32 v18, 0x200, v210
	v_and_b32_e32 v34, 0xffff0, v33
	v_lshrrev_b32_e32 v33, 1, v33
	v_xor_b32_e32 v17, v16, v96
	v_ashrrev_i32_e32 v18, 4, v18
	v_and_b32_e32 v33, 4, v33
	v_lshlrev_b32_e32 v17, 4, v17
	v_xor_b32_e32 v19, v18, v96
	v_or3_b32 v23, v34, v33, v23
	v_lshlrev_b32_e32 v16, 12, v16
	v_lshlrev_b32_e32 v19, 4, v19
	v_lshlrev_b32_e32 v21, 7, v210
	v_or_b32_e32 v32, 0x100, v38
	v_lshlrev_b32_e32 v23, 12, v23
	v_and_or_b32 v176, v17, s74, v16
	v_lshlrev_b32_e32 v16, 12, v18
	v_bitop3_b32 v22, v211, v96, s3 bitop3:0x1e
	v_or_b32_e32 v80, v36, v32
	v_or_b32_e32 v81, v23, v32
	v_and_or_b32 v32, v19, s74, v16
	v_and_b32_e32 v16, 0xfffffc00, v21
	s_lshl_b32 s48, s54, 12
	v_and_or_b32 v34, v22, s75, v16
	v_add_u32_e32 v16, 0x4000, v211
	s_add_u32 s48, s61, s48
	v_readfirstlane_b32 s82, v16
	v_add_u32_e32 v16, 0x6000, v211
	s_addc_u32 s49, s62, 0
	s_lshl_b32 s54, s54, 10
	s_mov_b32 m0, s82
	v_readfirstlane_b32 s82, v16
	v_add_u32_e32 v16, 0x8000, v211
	s_add_u32 s54, s65, s54
	global_load_lds_dwordx4 v176, s[48:49]
	s_mov_b32 m0, s82
	v_readfirstlane_b32 s82, v16
	s_addc_u32 s55, s66, 0
	global_load_lds_dwordx4 v32, s[48:49]
	v_mov_b32_e32 v35, v177
	s_mov_b32 m0, s82
	v_or_b32_e32 v36, v38, v36
	v_mov_b32_e32 v37, v177
	v_lshl_add_u64 v[40:41], s[54:55], 0, v[34:35]
	global_load_lds_dwordx4 v34, s[54:55]
	v_lshl_add_u64 v[16:17], s[48:49], 0, v[36:37]
	v_readfirstlane_b32 s54, v211
	v_lshl_add_u64 v[16:17], v[16:17], 0, s[4:5]
	s_mov_b32 m0, s54
	v_or_b32_e32 v38, v38, v23
	v_mov_b32_e32 v39, v177
	global_load_lds_dwordx4 v[16:17], off
	v_lshl_add_u64 v[16:17], s[48:49], 0, v[38:39]
	v_readfirstlane_b32 s54, v50
	v_lshl_add_u64 v[16:17], v[16:17], 0, s[4:5]
	s_mov_b32 m0, s54
	v_and_b32_e32 v208, 0xffffffe0, v20
	global_load_lds_dwordx4 v[16:17], off
	s_nop 0
	s_waitcnt vmcnt(0)
	v_mov_b32_e32 v24, v128
	v_mov_b32_e32 v25, v129
	v_mov_b32_e32 v26, v130
	v_mov_b32_e32 v27, v131
	v_mov_b32_e32 v28, v132
	v_mov_b32_e32 v29, v133
	v_mov_b32_e32 v30, v134
	v_mov_b32_e32 v31, v135
	v_mov_b32_e32 v42, v136
	v_mov_b32_e32 v43, v137
	v_mov_b32_e32 v44, v138
	v_mov_b32_e32 v45, v139
	v_mov_b32_e32 v46, v140
	v_mov_b32_e32 v47, v141
	v_mov_b32_e32 v48, v142
	v_mov_b32_e32 v49, v143
	v_mov_b32_e32 v50, v144
	v_mov_b32_e32 v51, v145
	v_mov_b32_e32 v52, v146
	v_mov_b32_e32 v53, v147
	v_mov_b32_e32 v54, v148
	v_mov_b32_e32 v55, v149
	v_mov_b32_e32 v56, v150
	v_mov_b32_e32 v57, v151
	v_mov_b32_e32 v58, v152
	v_mov_b32_e32 v59, v153
	v_mov_b32_e32 v60, v154
	v_mov_b32_e32 v61, v155
	v_mov_b32_e32 v62, v156
	v_mov_b32_e32 v63, v157
	v_mov_b32_e32 v64, v158
	v_mov_b32_e32 v65, v159
	v_mov_b32_e32 v16, v160
	v_mov_b32_e32 v17, v161
	v_mov_b32_e32 v18, v162
	v_mov_b32_e32 v19, v163
	v_mov_b32_e32 v68, v164
	v_mov_b32_e32 v69, v165
	v_mov_b32_e32 v70, v166
	v_mov_b32_e32 v71, v167
	v_mov_b32_e32 v20, v168
	v_mov_b32_e32 v21, v169
	v_mov_b32_e32 v22, v170
	v_mov_b32_e32 v23, v171
	v_mov_b32_e32 v72, v172
	v_mov_b32_e32 v73, v173
	v_mov_b32_e32 v74, v174
	v_mov_b32_e32 v75, v175
	v_and_b32_e32 v133, 0xffff0000, v24
	v_and_b32_e32 v155, 0xffff0000, v25
	v_lshlrev_b32_e32 v132, 16, v24
	v_mul_f32_e32 v24, v133, v133
	v_lshlrev_b32_e32 v154, 16, v25
	v_mul_f32_e32 v25, v155, v155
	v_fmac_f32_e32 v24, v132, v132
	v_fmac_f32_e32 v25, v154, v154
	v_and_b32_e32 v163, 0xffff0000, v26
	v_add_f32_e32 v24, v24, v25
	v_lshlrev_b32_e32 v162, 16, v26
	v_mul_f32_e32 v25, v163, v163
	v_fmac_f32_e32 v25, v162, v162
	v_and_b32_e32 v165, 0xffff0000, v27
	v_add_f32_e32 v24, v25, v24
	v_lshlrev_b32_e32 v164, 16, v27
	v_mul_f32_e32 v25, v165, v165
	v_fmac_f32_e32 v25, v164, v164
	v_and_b32_e32 v167, 0xffff0000, v28
	v_add_f32_e32 v24, v25, v24
	v_lshlrev_b32_e32 v166, 16, v28
	v_mul_f32_e32 v25, v167, v167
	v_fmac_f32_e32 v25, v166, v166
	v_and_b32_e32 v169, 0xffff0000, v29
	v_add_f32_e32 v24, v25, v24
	v_lshlrev_b32_e32 v168, 16, v29
	v_mul_f32_e32 v25, v169, v169
	v_fmac_f32_e32 v25, v168, v168
	v_and_b32_e32 v125, 0xffff0000, v30
	v_add_f32_e32 v24, v25, v24
	v_lshlrev_b32_e32 v126, 16, v30
	v_mul_f32_e32 v25, v125, v125
	v_fmac_f32_e32 v25, v126, v126
	v_and_b32_e32 v127, 0xffff0000, v31
	v_add_f32_e32 v24, v25, v24
	v_lshlrev_b32_e32 v170, 16, v31
	v_mul_f32_e32 v25, v127, v127
	v_fmac_f32_e32 v25, v170, v170
	v_and_b32_e32 v172, 0xffff0000, v42
	v_add_f32_e32 v24, v25, v24
	v_lshlrev_b32_e32 v171, 16, v42
	v_mul_f32_e32 v25, v172, v172
	v_fmac_f32_e32 v25, v171, v171
	v_and_b32_e32 v174, 0xffff0000, v43
	v_add_f32_e32 v24, v25, v24
	v_lshlrev_b32_e32 v173, 16, v43
	v_mul_f32_e32 v25, v174, v174
	v_fmac_f32_e32 v25, v173, v173
	v_and_b32_e32 v178, 0xffff0000, v44
	v_add_f32_e32 v24, v25, v24
	v_lshlrev_b32_e32 v175, 16, v44
	v_mul_f32_e32 v25, v178, v178
	v_fmac_f32_e32 v25, v175, v175
	v_and_b32_e32 v117, 0xffff0000, v45
	v_add_f32_e32 v24, v25, v24
	v_lshlrev_b32_e32 v118, 16, v45
	v_mul_f32_e32 v25, v117, v117
	v_fmac_f32_e32 v25, v118, v118
	v_and_b32_e32 v119, 0xffff0000, v46
	v_add_f32_e32 v24, v25, v24
	v_lshlrev_b32_e32 v120, 16, v46
	v_mul_f32_e32 v25, v119, v119
	v_fmac_f32_e32 v25, v120, v120
	v_and_b32_e32 v121, 0xffff0000, v47
	v_add_f32_e32 v24, v25, v24
; __device__ __forceinline__ void attn_body(const u16* __restrict__ Qb, const u16* __restrict__ Kn, const u16* __restrict__ Kr,
;                                           u16* __restrict__ Ob, char* lds, int tid, const float* __restrict__ gq_, const float* __restrict__ tab_, int qpos0, float negM) {
;     ...
;     for (int d0 = 0; d0 < 12; ++d0)
; #pragma unroll
;       for (int e = 0; e < 4; ++e) { const float a = bflo(qw[d0][e]), b = bfhi(qw[d0][e]); ss += a * a + b * b; }
;     { auto rr = __builtin_amdgcn_permlane32_swap(__float_as_uint(ss), __float_as_uint(ss), false, false);
;       ss = __uint_as_float(rr[0]) + __uint_as_float(rr[1]); }
;     const float rq = rsqrtf(ss * (1.f / 192.f) + EPS) * QSCALE;
;     const float* gq = gq_ + hi * 8;
; #pragma unroll
;     for (int d0 = 0; d0 < 8; ++d0) {
;       const f32x4 g0 = *reinterpret_cast<const f32x4*>(gq + d0 * 16), g1 = *reinterpret_cast<const f32x4*>(gq + d0 * 16 + 4);
;       const u32x4 w = qw[d0];
;       const u32x4 o = {cvtpk(bflo(w[0]) * rq * g0[0], bfhi(w[0]) * rq * g0[1]), cvtpk(bflo(w[1]) * rq * g0[2], bfhi(w[1]) * rq * g0[3]),
;                        cvtpk(bflo(w[2]) * rq * g1[0], bfhi(w[2]) * rq * g1[1]), cvtpk(bflo(w[3]) * rq * g1[2], bfhi(w[3]) * rq * g1[3])};
;       qr[d0] = *reinterpret_cast<const bf16x8*>(&o); }
;     const float* tcp = tab_ + (size_t)(qpos0 + wid * 32 + r32) * 32 + hi * 8; const float* tsp = tcp + SEQ * 32;
; #pragma unroll
;     for (int dd = 0; dd < 2; ++dd) {
;       float x1[8], x2[8], c_[8], s_[8];
;       { const f32x4 ga = *reinterpret_cast<const f32x4*>(gq + 128 + dd * 16), gb = *reinterpret_cast<const f32x4*>(gq + 128 + dd * 16 + 4);
;         const f32x4 gc = *reinterpret_cast<const f32x4*>(gq + 160 + dd * 16), gd = *reinterpret_cast<const f32x4*>(gq + 160 + dd * 16 + 4);
;         const f32x4 ca = *reinterpret_cast<const f32x4*>(tcp + dd * 16), cb = *reinterpret_cast<const f32x4*>(tcp + dd * 16 + 4);
;         const f32x4 sa = *reinterpret_cast<const f32x4*>(tsp + dd * 16), sb = *reinterpret_cast<const f32x4*>(tsp + dd * 16 + 4);
;         const u32x4 w1 = qw[8 + dd], w2 = qw[10 + dd];
; #pragma unroll
;         for (int e = 0; e < 4; ++e) {
;           const float g1lo = e < 2 ? ga[2 * e] : gb[2 * e - 4], g1hi = e < 2 ? ga[2 * e + 1] : gb[2 * e - 3];
;           const float g2lo = e < 2 ? gc[2 * e] : gd[2 * e - 4], g2hi = e < 2 ? gc[2 * e + 1] : gd[2 * e - 3];
	v_lshlrev_b32_e32 v122, 16, v47
	v_mul_f32_e32 v25, v121, v121
	v_fmac_f32_e32 v25, v122, v122
	v_and_b32_e32 v123, 0xffff0000, v48
	v_add_f32_e32 v24, v25, v24
	v_lshlrev_b32_e32 v124, 16, v48
	v_mul_f32_e32 v25, v123, v123
	v_fmac_f32_e32 v25, v124, v124
	v_and_b32_e32 v110, 0xffff0000, v49
	v_add_f32_e32 v24, v25, v24
	v_lshlrev_b32_e32 v111, 16, v49
	v_mul_f32_e32 v25, v110, v110
	v_fmac_f32_e32 v25, v111, v111
	v_and_b32_e32 v112, 0xffff0000, v50
	v_add_f32_e32 v24, v25, v24
	v_lshlrev_b32_e32 v113, 16, v50
	v_mul_f32_e32 v25, v112, v112
	v_fmac_f32_e32 v25, v113, v113
	v_and_b32_e32 v114, 0xffff0000, v51
	v_add_f32_e32 v24, v25, v24
	v_lshlrev_b32_e32 v115, 16, v51
	v_mul_f32_e32 v25, v114, v114
	v_fmac_f32_e32 v25, v115, v115
	v_and_b32_e32 v90, 0xffff0000, v52
	v_add_f32_e32 v24, v25, v24
	v_lshlrev_b32_e32 v116, 16, v52
	v_mul_f32_e32 v25, v90, v90
	v_fmac_f32_e32 v25, v116, v116
	v_and_b32_e32 v94, 0xffff0000, v53
	v_add_f32_e32 v24, v25, v24
	v_lshlrev_b32_e32 v98, 16, v53
	v_mul_f32_e32 v25, v94, v94
	v_fmac_f32_e32 v25, v98, v98
	v_and_b32_e32 v99, 0xffff0000, v54
	v_add_f32_e32 v24, v25, v24
	v_lshlrev_b32_e32 v103, 16, v54
	v_mul_f32_e32 v25, v99, v99
	v_fmac_f32_e32 v25, v103, v103
	v_and_b32_e32 v104, 0xffff0000, v55
	v_add_f32_e32 v24, v25, v24
	v_lshlrev_b32_e32 v106, 16, v55
	v_mul_f32_e32 v25, v104, v104
	v_fmac_f32_e32 v25, v106, v106
	v_and_b32_e32 v107, 0xffff0000, v56
	v_add_f32_e32 v24, v25, v24
	v_lshlrev_b32_e32 v108, 16, v56
	v_mul_f32_e32 v25, v107, v107
	v_fmac_f32_e32 v25, v108, v108
	v_and_b32_e32 v82, 0xffff0000, v57
	v_add_f32_e32 v24, v25, v24
	v_lshlrev_b32_e32 v109, 16, v57
	v_mul_f32_e32 v25, v82, v82
	v_fmac_f32_e32 v25, v109, v109
	v_and_b32_e32 v83, 0xffff0000, v58
	v_add_f32_e32 v24, v25, v24
	v_lshlrev_b32_e32 v84, 16, v58
	v_mul_f32_e32 v25, v83, v83
	v_fmac_f32_e32 v25, v84, v84
	v_and_b32_e32 v85, 0xffff0000, v59
	v_add_f32_e32 v24, v25, v24
	v_lshlrev_b32_e32 v86, 16, v59
	v_mul_f32_e32 v25, v85, v85
	v_fmac_f32_e32 v25, v86, v86
	v_and_b32_e32 v87, 0xffff0000, v60
	v_add_f32_e32 v24, v25, v24
	v_lshlrev_b32_e32 v88, 16, v60
	v_mul_f32_e32 v25, v87, v87
	v_fmac_f32_e32 v25, v88, v88
	v_and_b32_e32 v89, 0xffff0000, v61
	v_add_f32_e32 v24, v25, v24
	v_lshlrev_b32_e32 v91, 16, v61
	v_mul_f32_e32 v25, v89, v89
	v_fmac_f32_e32 v25, v91, v91
	v_and_b32_e32 v92, 0xffff0000, v62
	v_add_f32_e32 v24, v25, v24
	v_lshlrev_b32_e32 v95, 16, v62
	v_mul_f32_e32 v25, v92, v92
	v_fmac_f32_e32 v25, v95, v95
	v_and_b32_e32 v93, 0xffff0000, v63
	v_add_f32_e32 v24, v25, v24
	v_lshlrev_b32_e32 v100, 16, v63
	v_mul_f32_e32 v25, v93, v93
	v_fmac_f32_e32 v25, v100, v100
	v_and_b32_e32 v97, 0xffff0000, v64
	v_add_f32_e32 v24, v25, v24
	v_lshlrev_b32_e32 v101, 16, v64
	v_mul_f32_e32 v25, v97, v97
	v_fmac_f32_e32 v25, v101, v101
	v_and_b32_e32 v102, 0xffff0000, v65
	v_add_f32_e32 v24, v25, v24
	v_lshlrev_b32_e32 v105, 16, v65
	v_mul_f32_e32 v25, v102, v102
	v_fmac_f32_e32 v25, v105, v105
	v_and_b32_e32 v58, 32, v96
	v_add_u32_e32 v254, 0x1e800, v58
	v_add_f32_e32 v146, v25, v24
	ds_read_b128 v[24:27], v254 offset:16
	ds_read_b128 v[28:31], v254
	ds_read_b128 v[134:137], v254 offset:80
	ds_read_b128 v[138:141], v254 offset:64
	s_and_b32 s81, s0, 0x700
	v_add_u32_e32 v42, s81, v66
	v_ashrrev_i32_e32 v43, 31, v42
	v_lshlrev_b64 v[42:43], 7, v[42:43]
	v_lshl_add_u64 v[66:67], s[8:9], 0, v[42:43]
	v_and_b32_e32 v42, 0xffff0000, v75
	v_and_b32_e32 v46, 0xffff0000, v74
	v_lshlrev_b32_e32 v44, 16, v75
	v_lshlrev_b32_e32 v48, 16, v74
	v_mov_b32_e32 v52, v42
	v_mov_b32_e32 v53, v46
	v_mov_b32_e32 v50, v44
	v_mov_b32_e32 v51, v48
	v_pk_mul_f32 v[52:53], v[52:53], v[52:53]
	v_and_b32_e32 v54, 0xffff0000, v72
	v_pk_fma_f32 v[78:79], v[50:51], v[50:51], v[52:53]
	v_and_b32_e32 v50, 0xffff0000, v73
	v_lshlrev_b32_e32 v52, 16, v73
	v_lshlrev_b32_e32 v56, 16, v72
	v_mov_b32_e32 v62, v50
	v_mov_b32_e32 v63, v54
	v_mov_b32_e32 v60, v52
	v_mov_b32_e32 v61, v56
	v_pk_mul_f32 v[62:63], v[62:63], v[62:63]
	v_lshlrev_b32_e32 v53, 16, v69
	v_and_b32_e32 v51, 0xffff0000, v69
	v_lshlrev_b32_e32 v57, 16, v68
	v_and_b32_e32 v55, 0xffff0000, v68
	v_pk_fma_f32 v[68:69], v[60:61], v[60:61], v[62:63]
	v_and_b32_e32 v60, 0xffff0000, v23
	v_lshlrev_b32_e32 v64, 16, v22
	v_and_b32_e32 v22, 0xffff0000, v22
	v_lshlrev_b32_e32 v45, 16, v71
	v_and_b32_e32 v43, 0xffff0000, v71
	v_lshlrev_b32_e32 v49, 16, v70
	v_and_b32_e32 v47, 0xffff0000, v70
	v_lshlrev_b32_e32 v62, 16, v23
	v_mov_b32_e32 v70, v60
	v_mov_b32_e32 v71, v22
	v_lshlrev_b32_e32 v63, 16, v19
	v_and_b32_e32 v61, 0xffff0000, v19
	v_lshlrev_b32_e32 v65, 16, v18
	v_and_b32_e32 v23, 0xffff0000, v18
	v_mov_b32_e32 v18, v62
	v_mov_b32_e32 v19, v64
	v_pk_mul_f32 v[70:71], v[70:71], v[70:71]
	v_and_b32_e32 v75, 0xffff0000, v16
	v_and_b32_e32 v74, 0xffff0000, v20
	v_pk_fma_f32 v[128:129], v[18:19], v[18:19], v[70:71]
	v_lshlrev_b32_e32 v72, 16, v21
	v_and_b32_e32 v71, 0xffff0000, v17
	v_and_b32_e32 v70, 0xffff0000, v21
	v_lshlrev_b32_e32 v77, 16, v16
	v_lshlrev_b32_e32 v76, 16, v20
	v_pk_mul_f32 v[20:21], v[74:75], v[74:75]
	v_lshlrev_b32_e32 v73, 16, v17
	v_pk_mul_f32 v[18:19], v[70:71], v[70:71]
	v_pk_fma_f32 v[20:21], v[76:77], v[76:77], v[20:21]
	v_mul_f32_e32 v152, v65, v65
	v_pk_fma_f32 v[130:131], v[72:73], v[72:73], v[18:19]
	v_add_f32_e32 v21, v21, v146
	v_mul_f32_e32 v151, v63, v63
	v_fmac_f32_e32 v152, v23, v23
	v_add_f32_e32 v21, v131, v21
	v_mul_f32_e32 v150, v57, v57
	v_fmac_f32_e32 v151, v61, v61
	v_add_f32_e32 v21, v152, v21
	v_mul_f32_e32 v149, v53, v53
	v_fmac_f32_e32 v150, v55, v55
	v_add_f32_e32 v21, v151, v21
	v_mul_f32_e32 v148, v49, v49
	v_fmac_f32_e32 v149, v51, v51
; __device__ __forceinline__ float bflo(unsigned w) { return __uint_as_float(w << 16); }
; __device__ __forceinline__ float bfhi(unsigned w) { return __uint_as_float(w & 0xffff0000u); }
; __device__ __forceinline__ void attn_body(const u16* __restrict__ Qb, const u16* __restrict__ Kn, const u16* __restrict__ Kr,
;                                           u16* __restrict__ Ob, char* lds, int tid, const float* __restrict__ gq_, const float* __restrict__ tab_, int qpos0, float negM) {
;     ...
;     { auto rr = __builtin_amdgcn_permlane32_swap(__float_as_uint(ss), __float_as_uint(ss), false, false);
;       ss = __uint_as_float(rr[0]) + __uint_as_float(rr[1]); }
;     const float rq = rsqrtf(ss * (1.f / 192.f) + EPS) * QSCALE;
;     const float* gq = gq_ + hi * 8;
; #pragma unroll
;     for (int d0 = 0; d0 < 8; ++d0) {
;       const f32x4 g0 = *reinterpret_cast<const f32x4*>(gq + d0 * 16), g1 = *reinterpret_cast<const f32x4*>(gq + d0 * 16 + 4);
;       const u32x4 w = qw[d0];
;       const u32x4 o = {cvtpk(bflo(w[0]) * rq * g0[0], bfhi(w[0]) * rq * g0[1]), cvtpk(bflo(w[1]) * rq * g0[2], bfhi(w[1]) * rq * g0[3]),
;                        cvtpk(bflo(w[2]) * rq * g1[0], bfhi(w[2]) * rq * g1[1]), cvtpk(bflo(w[3]) * rq * g1[2], bfhi(w[3]) * rq * g1[3])};
;       qr[d0] = *reinterpret_cast<const bf16x8*>(&o); }
;     const float* tcp = tab_ + (size_t)(qpos0 + wid * 32 + r32) * 32 + hi * 8; const float* tsp = tcp + SEQ * 32;
; #pragma unroll
;     for (int dd = 0; dd < 2; ++dd) {
;       float x1[8], x2[8], c_[8], s_[8];
;       { const f32x4 ga = *reinterpret_cast<const f32x4*>(gq + 128 + dd * 16), gb = *reinterpret_cast<const f32x4*>(gq + 128 + dd * 16 + 4);
;         const f32x4 gc = *reinterpret_cast<const f32x4*>(gq + 160 + dd * 16), gd = *reinterpret_cast<const f32x4*>(gq + 160 + dd * 16 + 4);
;         const f32x4 ca = *reinterpret_cast<const f32x4*>(tcp + dd * 16), cb = *reinterpret_cast<const f32x4*>(tcp + dd * 16 + 4);
;         const f32x4 sa = *reinterpret_cast<const f32x4*>(tsp + dd * 16), sb = *reinterpret_cast<const f32x4*>(tsp + dd * 16 + 4);
	v_add_f32_e32 v21, v150, v21
	v_mul_f32_e32 v147, v45, v45
	v_fmac_f32_e32 v148, v47, v47
	v_add_f32_e32 v21, v149, v21
	v_fmac_f32_e32 v147, v43, v43
	v_add_f32_e32 v21, v148, v21
	v_add_f32_e32 v21, v147, v21
	v_add_f32_e32 v20, v20, v21
	v_add_f32_e32 v20, v130, v20
	v_add_f32_e32 v20, v129, v20
	v_add_f32_e32 v20, v128, v20
	v_add_f32_e32 v20, v69, v20
	v_add_f32_e32 v20, v68, v20
	v_add_f32_e32 v20, v79, v20
	v_add_f32_e32 v20, v78, v20
	v_mov_b32_e32 v21, v20
	s_nop 1
	v_permlane32_swap_b32_e32 v20, v21
	ds_read_b128 v[16:19], v254 offset:144
	ds_read_b128 v[142:145], v254 offset:128
	v_add_f32_e32 v20, v20, v21
	v_mov_b32_e32 v21, 0x358637bd
	v_fmamk_f32 v20, v20, 0x3baaaaab, v21
	v_mul_f32_e32 v21, 0x4b800000, v20
	v_cmp_gt_f32_e32 vcc, s77, v20
	ds_read_b128 v[146:149], v254 offset:208
	ds_read_b128 v[150:153], v254 offset:192
	v_cndmask_b32_e32 v20, v20, v21, vcc
	v_rsq_f32_e32 v20, v20
	v_mov_b32_e32 v59, v177
	v_lshl_add_u64 v[68:69], v[66:67], 0, v[58:59]
	v_lshl_add_u64 v[78:79], v[68:69], 0, s[10:11]
	global_load_dwordx4 v[212:215], v[78:79], off
	global_load_dwordx4 v[216:219], v[68:69], off offset:16
	global_load_dwordx4 v[220:223], v[68:69], off
	global_load_dwordx4 v[224:227], v[78:79], off offset:16
	global_load_dwordx4 v[228:231], v[78:79], off offset:64
	global_load_dwordx4 v[232:235], v[68:69], off offset:80
	global_load_dwordx4 v[236:239], v[68:69], off offset:64
	global_load_dwordx4 v[240:243], v[78:79], off offset:80
	v_mul_f32_e32 v21, 0x45800000, v20
	v_cndmask_b32_e32 v20, v20, v21, vcc
	v_mul_f32_e32 v20, 0x3dd53b94, v20
	v_mul_f32_e32 v21, v20, v132
	s_waitcnt vmcnt(0) lgkmcnt(0)
	v_mul_f32_e32 v21, v28, v21
	v_mul_f32_e32 v28, v20, v133
	v_mul_f32_e32 v28, v29, v28
	s_nop 0
	v_cvt_pk_bf16_f32 v128, v21, v28
	v_mul_f32_e32 v21, v20, v154
	v_mul_f32_e32 v21, v30, v21
	v_mul_f32_e32 v28, v20, v155
	v_mul_f32_e32 v28, v31, v28
	s_nop 0
	v_cvt_pk_bf16_f32 v129, v21, v28
	v_mul_f32_e32 v21, v20, v162
	ds_read_b128 v[154:157], v254 offset:272
	ds_read_b128 v[158:161], v254 offset:256
	v_mul_f32_e32 v21, v24, v21
	v_mul_f32_e32 v24, v20, v163
	v_mul_f32_e32 v24, v25, v24
	s_nop 0
	v_cvt_pk_bf16_f32 v130, v21, v24
	v_mul_f32_e32 v24, v20, v165
	v_mul_f32_e32 v21, v20, v164
	v_mul_f32_e32 v24, v27, v24
	v_mul_f32_e32 v21, v26, v21
	s_nop 0
	v_cvt_pk_bf16_f32 v131, v21, v24
	v_mul_f32_e32 v24, v20, v167
	v_mul_f32_e32 v21, v20, v166
	v_mul_f32_e32 v24, v139, v24
	v_mul_f32_e32 v21, v138, v21
	s_nop 0
	v_cvt_pk_bf16_f32 v132, v21, v24
	v_mul_f32_e32 v24, v20, v169
	v_mul_f32_e32 v21, v20, v168
	v_mul_f32_e32 v24, v141, v24
	v_mul_f32_e32 v21, v140, v21
	s_nop 0
	v_cvt_pk_bf16_f32 v133, v21, v24
	ds_read_b128 v[24:27], v254 offset:336
	ds_read_b128 v[28:31], v254 offset:320
	v_mul_f32_e32 v21, v20, v126
	v_mul_f32_e32 v21, v134, v21
	v_mul_f32_e32 v59, v20, v125
	v_mul_f32_e32 v59, v135, v59
	s_nop 0
	v_cvt_pk_bf16_f32 v134, v21, v59
	v_mul_f32_e32 v21, v20, v170
	v_mul_f32_e32 v21, v136, v21
	v_mul_f32_e32 v59, v20, v127
	v_mul_f32_e32 v59, v137, v59
	s_nop 0
	v_cvt_pk_bf16_f32 v135, v21, v59
	v_mul_f32_e32 v21, v20, v171
	v_mul_f32_e32 v59, v20, v172
	ds_read_b128 v[162:165], v254 offset:400
	ds_read_b128 v[166:169], v254 offset:384
	v_lshl_add_u64 v[66:67], v[68:69], 0, s[12:13]
	v_and_b32_e32 v209, 63, v96
	v_and_b32_e32 v206, 31, v96
	v_mov_b32_e32 v33, v177
	s_mov_b32 s50, 0
	v_mul_f32_e32 v21, v21, v142
	v_mul_f32_e32 v59, v59, v143
	s_nop 0
	v_cvt_pk_bf16_f32 v136, v21, v59
	v_mul_f32_e32 v21, v20, v173
	v_mul_f32_e32 v21, v21, v144
	v_mul_f32_e32 v59, v20, v174
	v_mul_f32_e32 v59, v59, v145
	s_nop 0
	v_cvt_pk_bf16_f32 v137, v21, v59
	v_mul_f32_e32 v21, v20, v175
	v_mul_f32_e32 v16, v21, v16
	v_mul_f32_e32 v21, v20, v178
	v_mul_f32_e32 v17, v21, v17
	s_nop 0
	v_cvt_pk_bf16_f32 v138, v16, v17
	v_mul_f32_e32 v16, v20, v118
	v_mul_f32_e32 v16, v16, v18
	v_mul_f32_e32 v17, v20, v117
	v_mul_f32_e32 v17, v17, v19
	s_nop 0
	v_cvt_pk_bf16_f32 v139, v16, v17
	v_mul_f32_e32 v16, v20, v120
	v_mul_f32_e32 v16, v16, v150
	v_mul_f32_e32 v17, v20, v119
	v_mul_f32_e32 v17, v17, v151
	s_nop 0
	v_cvt_pk_bf16_f32 v140, v16, v17
	v_mul_f32_e32 v16, v20, v122
	v_mul_f32_e32 v16, v16, v152
	v_mul_f32_e32 v17, v20, v121
	v_mul_f32_e32 v17, v17, v153
	s_nop 0
	v_cvt_pk_bf16_f32 v141, v16, v17
	v_mul_f32_e32 v16, v20, v124
	v_mul_f32_e32 v16, v16, v146
	v_mul_f32_e32 v17, v20, v123
	v_mul_f32_e32 v17, v17, v147
	s_nop 0
	v_cvt_pk_bf16_f32 v142, v16, v17
	v_mul_f32_e32 v16, v20, v111
	v_mul_f32_e32 v16, v16, v148
	v_mul_f32_e32 v17, v20, v110
	v_mul_f32_e32 v17, v17, v149
	s_nop 0
	v_cvt_pk_bf16_f32 v143, v16, v17
	v_mul_f32_e32 v16, v20, v113
	s_waitcnt vmcnt(0) lgkmcnt(0)
; __device__ __forceinline__ void attn_body(const u16* __restrict__ Qb, const u16* __restrict__ Kn, const u16* __restrict__ Kr,
;                                           u16* __restrict__ Ob, char* lds, int tid, const float* __restrict__ gq_, const float* __restrict__ tab_, int qpos0, float negM) {
;     ...
;     for (int d0 = 0; d0 < 8; ++d0) {
;       const f32x4 g0 = *reinterpret_cast<const f32x4*>(gq + d0 * 16), g1 = *reinterpret_cast<const f32x4*>(gq + d0 * 16 + 4);
;       const u32x4 w = qw[d0];
;       const u32x4 o = {cvtpk(bflo(w[0]) * rq * g0[0], bfhi(w[0]) * rq * g0[1]), cvtpk(bflo(w[1]) * rq * g0[2], bfhi(w[1]) * rq * g0[3]),
;                        cvtpk(bflo(w[2]) * rq * g1[0], bfhi(w[2]) * rq * g1[1]), cvtpk(bflo(w[3]) * rq * g1[2], bfhi(w[3]) * rq * g1[3])};
;       qr[d0] = *reinterpret_cast<const bf16x8*>(&o); }
;     const float* tcp = tab_ + (size_t)(qpos0 + wid * 32 + r32) * 32 + hi * 8; const float* tsp = tcp + SEQ * 32;
; #pragma unroll
;     for (int dd = 0; dd < 2; ++dd) {
;       float x1[8], x2[8], c_[8], s_[8];
;       { const f32x4 ga = *reinterpret_cast<const f32x4*>(gq + 128 + dd * 16), gb = *reinterpret_cast<const f32x4*>(gq + 128 + dd * 16 + 4);
;         const f32x4 gc = *reinterpret_cast<const f32x4*>(gq + 160 + dd * 16), gd = *reinterpret_cast<const f32x4*>(gq + 160 + dd * 16 + 4);
;         const f32x4 ca = *reinterpret_cast<const f32x4*>(tcp + dd * 16), cb = *reinterpret_cast<const f32x4*>(tcp + dd * 16 + 4);
;         const f32x4 sa = *reinterpret_cast<const f32x4*>(tsp + dd * 16), sb = *reinterpret_cast<const f32x4*>(tsp + dd * 16 + 4);
;         const u32x4 w1 = qw[8 + dd], w2 = qw[10 + dd];
; #pragma unroll
;         for (int e = 0; e < 4; ++e) {
;           const float g1lo = e < 2 ? ga[2 * e] : gb[2 * e - 4], g1hi = e < 2 ? ga[2 * e + 1] : gb[2 * e - 3];
;           const float g2lo = e < 2 ? gc[2 * e] : gd[2 * e - 4], g2hi = e < 2 ? gc[2 * e + 1] : gd[2 * e - 3];
;           x1[2 * e] = bflo(w1[e]) * rq * g1lo; x1[2 * e + 1] = bfhi(w1[e]) * rq * g1hi;
;           x2[2 * e] = bflo(w2[e]) * rq * g2lo; x2[2 * e + 1] = bfhi(w2[e]) * rq * g2hi;
;           c_[2 * e] = e < 2 ? ca[2 * e] : cb[2 * e - 4]; c_[2 * e + 1] = e < 2 ? ca[2 * e + 1] : cb[2 * e - 3];
;           s_[2 * e] = e < 2 ? sa[2 * e] : sb[2 * e - 4]; s_[2 * e + 1] = e < 2 ? sa[2 * e + 1] : sb[2 * e - 3]; } }
;       float y1[8], y2[8];
; #pragma unroll
	v_mul_f32_e32 v16, v16, v158
	v_mul_f32_e32 v17, v20, v112
	v_mul_f32_e32 v17, v17, v159
	s_nop 0
	v_cvt_pk_bf16_f32 v144, v16, v17
	v_mul_f32_e32 v16, v20, v115
	v_mul_f32_e32 v16, v16, v160
	v_mul_f32_e32 v17, v20, v114
	ds_read_b128 v[118:121], v254 offset:464
	ds_read_b128 v[122:125], v254 offset:448
	v_mul_f32_e32 v17, v17, v161
	s_nop 0
	v_cvt_pk_bf16_f32 v145, v16, v17
	v_mul_f32_e32 v16, v20, v116
	v_mul_f32_e32 v16, v16, v154
	v_mul_f32_e32 v17, v20, v90
	v_mul_f32_e32 v17, v17, v155
	s_nop 0
	v_cvt_pk_bf16_f32 v146, v16, v17
	v_mul_f32_e32 v16, v20, v98
	v_mul_f32_e32 v16, v16, v156
	v_mul_f32_e32 v17, v20, v94
	v_mul_f32_e32 v17, v17, v157
	s_nop 0
	v_cvt_pk_bf16_f32 v147, v16, v17
	v_mul_f32_e32 v16, v20, v103
	v_mul_f32_e32 v16, v16, v28
	v_mul_f32_e32 v17, v20, v99
	v_mul_f32_e32 v17, v17, v29
	s_nop 0
	v_cvt_pk_bf16_f32 v148, v16, v17
	v_mul_f32_e32 v16, v20, v106
	ds_read_b128 v[110:113], v254 offset:656
	ds_read_b128 v[114:117], v254 offset:640
	ds_read_b128 v[170:173], v254 offset:528
	ds_read_b128 v[178:181], v254 offset:512
	v_mul_f32_e32 v16, v16, v30
	v_mul_f32_e32 v17, v20, v104
	v_mul_f32_e32 v17, v17, v31
	s_nop 0
	v_cvt_pk_bf16_f32 v149, v16, v17
	v_mul_f32_e32 v16, v20, v108
	v_mul_f32_e32 v16, v16, v24
	v_mul_f32_e32 v17, v20, v107
	v_add_co_u32_e32 v98, vcc, s78, v68
	v_mul_f32_e32 v17, v17, v25
	s_nop 0
	v_cvt_pk_bf16_f32 v150, v16, v17
	v_mul_f32_e32 v16, v20, v109
	v_addc_co_u32_e32 v99, vcc, 0, v69, vcc
	v_mul_f32_e32 v21, v16, v26
	v_mov_b32_e32 v28, v212
	v_mov_b32_e32 v29, v213
	v_mov_b32_e32 v30, v214
	v_mov_b32_e32 v31, v215
	v_mov_b32_e32 v16, v216
	v_mov_b32_e32 v17, v217
	v_mov_b32_e32 v18, v218
	v_mov_b32_e32 v19, v219
	v_mov_b32_e32 v106, v220
	v_mov_b32_e32 v107, v221
	v_mov_b32_e32 v108, v222
	v_mov_b32_e32 v109, v223
	v_mul_f32_e32 v24, v20, v82
	v_mul_f32_e32 v24, v24, v27
	s_nop 0
	v_cvt_pk_bf16_f32 v151, v21, v24
	v_mul_f32_e32 v21, v20, v84
	v_mul_f32_e32 v21, v21, v166
	v_mul_f32_e32 v24, v20, v83
	v_mul_f32_e32 v24, v24, v167
	s_nop 0
	v_cvt_pk_bf16_f32 v152, v21, v24
	v_mul_f32_e32 v21, v20, v86
	v_mul_f32_e32 v21, v21, v168
	v_mul_f32_e32 v24, v20, v85
	v_mul_f32_e32 v24, v24, v169
	s_nop 0
	v_cvt_pk_bf16_f32 v153, v21, v24
	v_mul_f32_e32 v21, v20, v88
	v_mul_f32_e32 v21, v21, v162
	v_mul_f32_e32 v24, v20, v87
	v_mul_f32_e32 v24, v24, v163
	s_nop 0
	v_cvt_pk_bf16_f32 v154, v21, v24
	v_mul_f32_e32 v21, v20, v91
	v_mul_f32_e32 v21, v21, v164
	v_mul_f32_e32 v24, v20, v89
	v_mul_f32_e32 v24, v24, v165
	s_nop 0
	v_cvt_pk_bf16_f32 v155, v21, v24
	v_mul_f32_e32 v21, v20, v95
	v_mul_f32_e32 v24, v20, v92
	v_mul_f32_e32 v59, v20, v93
	s_waitcnt vmcnt(0) lgkmcnt(0)
	v_mul_f32_e32 v21, v21, v122
	v_mul_f32_e32 v24, v24, v123
	s_nop 0
	v_cvt_pk_bf16_f32 v156, v21, v24
	v_mul_f32_e32 v21, v20, v100
	v_mul_f32_e32 v21, v21, v124
	v_mov_b32_e32 v24, v224
	v_mov_b32_e32 v25, v225
	v_mov_b32_e32 v26, v226
	v_mov_b32_e32 v27, v227
	v_mul_f32_e32 v59, v59, v125
	s_nop 0
	v_cvt_pk_bf16_f32 v157, v21, v59
	v_mul_f32_e32 v21, v20, v101
	v_mul_f32_e32 v21, v21, v118
	v_mul_f32_e32 v59, v20, v97
	v_mul_f32_e32 v59, v59, v119
	s_nop 0
	v_cvt_pk_bf16_f32 v158, v21, v59
	v_mul_f32_e32 v21, v20, v105
	v_mul_f32_e32 v21, v21, v120
	v_pk_mul_f32 v[74:75], v[20:21], v[74:75] op_sel_hi:[0,1]
	v_mul_f32_e32 v59, v20, v102
	v_pk_mul_f32 v[70:71], v[20:21], v[70:71] op_sel_hi:[0,1]
	v_mul_f32_e32 v59, v59, v121
	v_mov_b32_e32 v79, v178
	v_mov_b32_e32 v178, v115
	v_pk_mul_f32 v[90:91], v[74:75], v[178:179]
	v_mov_b32_e32 v75, v180
	v_mov_b32_e32 v180, v117
	v_pk_mul_f32 v[76:77], v[20:21], v[76:77] op_sel_hi:[0,1]
	v_mov_b32_e32 v78, v114
	v_pk_mul_f32 v[72:73], v[20:21], v[72:73] op_sel_hi:[0,1]
	v_mov_b32_e32 v74, v116
	v_pk_mul_f32 v[100:101], v[70:71], v[180:181]
	v_pk_mul_f32 v[64:65], v[20:21], v[64:65] op_sel_hi:[0,1]
	v_mov_b32_e32 v70, v110
	v_mov_b32_e32 v71, v170
	s_nop 0
	v_cvt_pk_bf16_f32 v159, v21, v59
	v_pk_mul_f32 v[78:79], v[76:77], v[78:79]
	v_pk_mul_f32 v[94:95], v[72:73], v[74:75]
	v_pk_mul_f32 v[102:103], v[64:65], v[70:71]
	ds_read_b128 v[70:73], v254 offset:720
	ds_read_b128 v[74:77], v254 offset:704
	ds_read_b128 v[82:85], v254 offset:592
	ds_read_b128 v[86:89], v254 offset:576
	v_pk_mul_f32 v[58:59], v[20:21], v[62:63] op_sel_hi:[0,1]
	v_mov_b32_e32 v62, v112
	v_mov_b32_e32 v63, v172
	v_pk_mul_f32 v[104:105], v[58:59], v[62:63]
	v_mov_b32_e32 v62, v28
	v_mov_b32_e32 v63, v106
	v_pk_mul_f32 v[62:63], v[78:79], v[62:63]
	v_pk_mul_f32 v[22:23], v[20:21], v[22:23] op_sel_hi:[0,1]
	v_pk_mul_f32 v[58:59], v[20:21], v[60:61] op_sel_hi:[0,1]
	v_sub_f32_e32 v21, v63, v62
	v_mov_b32_e32 v62, v106
	v_mov_b32_e32 v63, v28
	v_pk_mul_f32 v[62:63], v[78:79], v[62:63]
	v_mov_b32_e32 v106, v29
	v_mov_b32_e32 v172, v113
	v_add_f32_e32 v78, v62, v63
	v_pk_mul_f32 v[62:63], v[90:91], v[106:107]
	v_mov_b32_e32 v28, v107
	v_mov_b32_e32 v170, v111
	v_pk_mul_f32 v[110:111], v[58:59], v[172:173]
	v_mov_b32_e32 v58, v228
	v_mov_b32_e32 v59, v229
	v_mov_b32_e32 v60, v230
	v_mov_b32_e32 v61, v231
	v_sub_f32_e32 v79, v63, v62
	v_pk_mul_f32 v[28:29], v[90:91], v[28:29]
	v_mov_b32_e32 v62, v232
	v_mov_b32_e32 v63, v233
	v_mov_b32_e32 v64, v234
	v_mov_b32_e32 v65, v235
	v_mov_b32_e32 v90, v236
	v_mov_b32_e32 v91, v237
	v_mov_b32_e32 v92, v238
	v_mov_b32_e32 v93, v239
	v_add_f32_e32 v97, v28, v29
	v_mov_b32_e32 v28, v30
	v_mov_b32_e32 v29, v108
	v_pk_mul_f32 v[28:29], v[94:95], v[28:29]
	v_pk_mul_f32 v[22:23], v[22:23], v[170:171]
	v_sub_f32_e32 v68, v29, v28
	v_mov_b32_e32 v28, v108
	v_mov_b32_e32 v29, v30
	v_pk_mul_f32 v[28:29], v[94:95], v[28:29]
	v_mov_b32_e32 v108, v31
	v_add_f32_e32 v69, v28, v29
	v_pk_mul_f32 v[28:29], v[100:101], v[108:109]
	v_mov_b32_e32 v30, v109
	v_sub_f32_e32 v94, v29, v28
	v_pk_mul_f32 v[28:29], v[100:101], v[30:31]
	s_nop 0
	v_cvt_pk_bf16_f32 v164, v21, v79
	v_pk_mul_f32 v[46:47], v[20:21], v[46:47] op_sel_hi:[0,1]
	v_add_f32_e32 v95, v28, v29
	v_mov_b32_e32 v28, v240
	v_mov_b32_e32 v29, v241
	v_mov_b32_e32 v30, v242
	v_mov_b32_e32 v31, v243
	v_mov_b32_e32 v67, v16
	v_pk_mul_f32 v[44:45], v[20:21], v[44:45] op_sel_hi:[0,1]
	s_waitcnt vmcnt(0) lgkmcnt(0)
	s_nop 0
	v_cvt_pk_bf16_f32 v165, v68, v94
	s_nop 0
	v_cvt_pk_bf16_f32 v160, v78, v97
	s_waitcnt vmcnt(0) lgkmcnt(0)
	v_mov_b32_e32 v66, v24
	v_pk_mul_f32 v[66:67], v[102:103], v[66:67]
	s_nop 0
	v_cvt_pk_bf16_f32 v161, v69, v95
	s_barrier
; __device__ __forceinline__ int v_rd_base(int lane) { return ((lane & 3) << 3) | (((lane >> 2) & 3) << 6) | (((lane >> 4) & 1) << 5) | (((lane >> 5) & 1) << 8); }
; #define AISSUE(k0, soff) do { const char* kb_ = (const char*)Kn + (size_t)(k0) * 4096; const char* rb_ = (const char*)Kr + (size_t)(k0) * 1024; \
;     char* st_ = lds + (soff) + tid * 16; \
;     GLDS(kb_ + vkn0, st_ + KOFF); GLDS(kb_ + vkn1, st_ + KOFF + 8192); GLDS(rb_ + vkr, st_ + KOFF + KROPE_OFF); \
;     GLDS(kb_ + vv0, st_); GLDS(kb_ + vv1, st_ + 8192); } while (0)
; __device__ __forceinline__ void qkt(f32x16& p0, f32x16& p1, const char* Ks, const bf16x8* qr, int r32, int hi, float negM) {
; #pragma unroll
;   for (int r = 0; r < 16; ++r) { p0[r] = negM; p1[r] = negM; }
;   __builtin_amdgcn_s_setprio(1);
;   const char* kn = Ks + r32 * 256; const int xn = r32 & 15;
; #pragma unroll
;   for (int d0 = 0; d0 < 8; ++d0) { const int off = ((d0 * 2 + hi) ^ xn) << 4;
;     bf16x8 b0 = *reinterpret_cast<const bf16x8*>(kn + off);
;     bf16x8 b1 = *reinterpret_cast<const bf16x8*>(kn + 32 * 256 + off);
;     p0 = __builtin_amdgcn_mfma_f32_32x32x16_bf16(b0, qr[d0], p0, 0, 0, 0);
;     p1 = __builtin_amdgcn_mfma_f32_32x32x16_bf16(b1, qr[d0], p1, 0, 0, 0); }
; __device__ __forceinline__ void attn_body(const u16* __restrict__ Qb, const u16* __restrict__ Kn, const u16* __restrict__ Kr,
;                                           u16* __restrict__ Ob, char* lds, int tid, const float* __restrict__ gq_, const float* __restrict__ tab_, int qpos0, float negM) {
;     ...
;       float y1[8], y2[8];
; #pragma unroll
;       for (int e = 0; e < 8; ++e) { y1[e] = x1[e] * c_[e] - x2[e] * s_[e]; y2[e] = x2[e] * c_[e] + x1[e] * s_[e]; }
;       const u32x4 o1 = {cvtpk(y1[0], y1[1]), cvtpk(y1[2], y1[3]), cvtpk(y1[4], y1[5]), cvtpk(y1[6], y1[7])};
;       const u32x4 o2 = {cvtpk(y2[0], y2[1]), cvtpk(y2[2], y2[3]), cvtpk(y2[4], y2[5]), cvtpk(y2[6], y2[7])};
;       qr[8 + dd] = *reinterpret_cast<const bf16x8*>(&o1); qr[10 + dd] = *reinterpret_cast<const bf16x8*>(&o2); }
;   }
;   const int vrb = (int)(uintptr_t)lds + v_rd_base(lane);
;   f32x16 pA0, pA1, pB0, pB1; bf16x8 pa0, pa1, pa2, pa3; constexpr int NT = SEQ / KVBLK;
;   WAITV(0); TBAR();
;   AISSUE(KVBLK, STG);
;   qkt(pA0, pA1, lds + KOFF, qr, r32, hi, negM); partialSM(pA0);
;   int prv = 0, cur = STG, nxt = 2 * STG;
	v_sub_f32_e32 v98, v67, v66
	v_mov_b32_e32 v66, v16
	v_mov_b32_e32 v67, v24
	v_pk_mul_f32 v[66:67], v[102:103], v[66:67]
	v_mov_b32_e32 v16, v25
	v_mov_b32_e32 v24, v17
	v_add_f32_e32 v99, v66, v67
	v_pk_mul_f32 v[66:67], v[22:23], v[16:17]
	v_pk_mul_f32 v[16:17], v[22:23], v[24:25]
	v_sub_f32_e32 v66, v67, v66
	v_add_f32_e32 v22, v16, v17
	v_mov_b32_e32 v16, v26
	v_mov_b32_e32 v17, v18
	v_pk_mul_f32 v[16:17], v[104:105], v[16:17]
	s_nop 0
	v_cvt_pk_bf16_f32 v162, v99, v22
	s_nop 0
	v_cvt_pk_bf16_f32 v166, v98, v66
	v_mov_b32_e32 v25, v88
	v_sub_f32_e32 v23, v17, v16
	v_mov_b32_e32 v16, v18
	v_mov_b32_e32 v17, v26
	v_pk_mul_f32 v[16:17], v[104:105], v[16:17]
	v_mov_b32_e32 v18, v27
	v_add_f32_e32 v24, v16, v17
	v_pk_mul_f32 v[16:17], v[110:111], v[18:19]
	v_mov_b32_e32 v26, v19
	v_sub_f32_e32 v18, v17, v16
	v_pk_mul_f32 v[16:17], v[110:111], v[26:27]
	s_nop 0
	v_cvt_pk_bf16_f32 v167, v23, v18
	v_mov_b32_e32 v18, v74
	v_add_f32_e32 v16, v16, v17
	s_nop 0
	v_cvt_pk_bf16_f32 v163, v24, v16
	v_pk_mul_f32 v[16:17], v[20:21], v[56:57] op_sel_hi:[0,1]
	v_mov_b32_e32 v19, v86
	v_pk_mul_f32 v[22:23], v[20:21], v[52:53] op_sel_hi:[0,1]
	v_mov_b32_e32 v24, v76
	v_pk_mul_f32 v[16:17], v[16:17], v[18:19]
	v_pk_mul_f32 v[18:19], v[20:21], v[54:55] op_sel_hi:[0,1]
	v_pk_mul_f32 v[22:23], v[22:23], v[24:25]
	v_pk_mul_f32 v[24:25], v[20:21], v[50:51] op_sel_hi:[0,1]
	v_pk_mul_f32 v[26:27], v[20:21], v[48:49] op_sel_hi:[0,1]
	v_mov_b32_e32 v48, v70
	v_mov_b32_e32 v49, v82
	v_pk_mul_f32 v[20:21], v[20:21], v[42:43] op_sel_hi:[0,1]
	v_mov_b32_e32 v42, v58
	v_mov_b32_e32 v43, v90
	v_pk_mul_f32 v[26:27], v[26:27], v[48:49]
	v_mov_b32_e32 v48, v72
	v_mov_b32_e32 v49, v84
	v_pk_mul_f32 v[42:43], v[16:17], v[42:43]
	v_mov_b32_e32 v86, v75
	v_pk_mul_f32 v[44:45], v[44:45], v[48:49]
	v_sub_f32_e32 v48, v43, v42
	v_mov_b32_e32 v42, v90
	v_mov_b32_e32 v43, v58
	v_pk_mul_f32 v[18:19], v[18:19], v[86:87]
	v_pk_mul_f32 v[16:17], v[16:17], v[42:43]
	v_mov_b32_e32 v90, v59
	v_add_f32_e32 v42, v16, v17
	v_pk_mul_f32 v[16:17], v[18:19], v[90:91]
	v_mov_b32_e32 v58, v91
	v_sub_f32_e32 v43, v17, v16
	v_pk_mul_f32 v[16:17], v[18:19], v[58:59]
	v_mov_b32_e32 v88, v77
	v_add_f32_e32 v18, v16, v17
	v_mov_b32_e32 v16, v60
	v_mov_b32_e32 v17, v92
	v_pk_mul_f32 v[16:17], v[22:23], v[16:17]
	v_pk_mul_f32 v[24:25], v[24:25], v[88:89]
	v_sub_f32_e32 v19, v17, v16
	v_mov_b32_e32 v16, v92
	v_mov_b32_e32 v17, v60
	v_pk_mul_f32 v[16:17], v[22:23], v[16:17]
	v_mov_b32_e32 v92, v61
	v_add_f32_e32 v22, v16, v17
	v_pk_mul_f32 v[16:17], v[24:25], v[92:93]
	v_mov_b32_e32 v60, v93
	v_sub_f32_e32 v23, v17, v16
	v_pk_mul_f32 v[16:17], v[24:25], v[60:61]
	v_mov_b32_e32 v82, v71
	v_add_f32_e32 v24, v16, v17
	v_mov_b32_e32 v16, v28
	v_mov_b32_e32 v17, v62
	v_pk_mul_f32 v[16:17], v[26:27], v[16:17]
	v_pk_mul_f32 v[46:47], v[46:47], v[82:83]
	v_sub_f32_e32 v25, v17, v16
	v_mov_b32_e32 v16, v62
	v_mov_b32_e32 v17, v28
	v_pk_mul_f32 v[16:17], v[26:27], v[16:17]
	v_mov_b32_e32 v62, v29
	v_add_f32_e32 v26, v16, v17
	v_pk_mul_f32 v[16:17], v[46:47], v[62:63]
	v_mov_b32_e32 v28, v63
	v_sub_f32_e32 v27, v17, v16
	v_pk_mul_f32 v[16:17], v[46:47], v[28:29]
	v_mov_b32_e32 v84, v73
	v_add_f32_e32 v28, v16, v17
	v_mov_b32_e32 v16, v30
	v_mov_b32_e32 v17, v64
	v_pk_mul_f32 v[16:17], v[44:45], v[16:17]
	v_pk_mul_f32 v[20:21], v[20:21], v[84:85]
	v_sub_f32_e32 v29, v17, v16
	v_mov_b32_e32 v16, v64
	v_mov_b32_e32 v17, v30
	v_pk_mul_f32 v[16:17], v[44:45], v[16:17]
	v_mov_b32_e32 v64, v31
	v_add_f32_e32 v44, v16, v17
	v_pk_mul_f32 v[16:17], v[20:21], v[64:65]
	v_mov_b32_e32 v30, v65
	v_sub_f32_e32 v45, v17, v16
	v_pk_mul_f32 v[16:17], v[20:21], v[30:31]
	s_nop 0
	v_cvt_pk_bf16_f32 v168, v42, v18
	v_lshlrev_b32_e32 v18, 1, v96
	v_add_f32_e32 v16, v16, v17
	v_lshlrev_b32_e32 v17, 4, v96
	s_nop 0
	v_cvt_pk_bf16_f32 v171, v44, v16
	v_lshlrev_b32_e32 v16, 3, v209
	v_and_b32_e32 v17, 0xc0, v17
	v_and_or_b32 v17, v16, 24, v17
	v_and_b32_e32 v18, 32, v18
	v_and_b32_e32 v16, 0x100, v16
	v_or3_b32 v212, v17, v18, v16
	s_nop 0
	v_cvt_pk_bf16_f32 v172, v48, v43
	s_nop 0
	v_cvt_pk_bf16_f32 v173, v19, v23
	s_nop 0
	v_cvt_pk_bf16_f32 v174, v25, v27
	s_nop 0
	v_cvt_pk_bf16_f32 v175, v29, v45
	s_nop 0
	v_cvt_pk_bf16_f32 v169, v22, v24
	s_nop 0
	v_cvt_pk_bf16_f32 v170, v26, v28
	v_add_u32_e32 v16, 0xe000, v211
	s_add_u32 s48, s48, 0x40000
	v_readfirstlane_b32 s51, v16
	v_add_u32_e32 v16, 0x10000, v211
	s_addc_u32 s49, s49, 0
	s_mov_b32 m0, s51
	v_readfirstlane_b32 s51, v16
	v_add_u32_e32 v19, 0x12000, v211
	global_load_lds_dwordx4 v176, s[48:49]
	s_mov_b32 m0, s51
	v_readfirstlane_b32 s51, v19
	v_add_u32_e32 v18, 0xa000, v211
	global_load_lds_dwordx4 v32, s[48:49]
	v_lshl_add_u64 v[16:17], v[40:41], 0, s[14:15]
	s_mov_b32 m0, s51
	v_readfirstlane_b32 s51, v18
	global_load_lds_dwordx4 v[16:17], off
	v_add_u32_e32 v16, 0xc000, v211
	s_mov_b32 m0, s51
	v_readfirstlane_b32 s51, v16
	global_load_lds_dwordx4 v80, s[48:49]
	s_mov_b32 m0, s51
	s_nop 0
	global_load_lds_dwordx4 v81, s[48:49]
	s_setprio 1
	v_bitop3_b32 v16, v207, v96, 15 bitop3:0x78
	v_lshlrev_b32_e32 v213, 8, v206
	v_lshlrev_b32_e32 v214, 4, v16
	v_or_b32_e32 v16, v213, v214
	ds_read_b128 v[40:43], v16 offset:16384
	ds_read_b128 v[44:47], v16 offset:24576
	v_and_b32_e32 v48, 15, v96
	v_lshlrev_b32_e32 v222, 7, v206
	s_waitcnt lgkmcnt(0)
	v_mfma_f32_32x32x16_bf16 v[16:31], v[40:43], v[128:131], v[0:15]
	v_bitop3_b32 v40, v207, v48, 2 bitop3:0x36
	v_lshlrev_b32_e32 v215, 4, v40
	v_mfma_f32_32x32x16_bf16 v[80:95], v[44:47], v[128:131], v[0:15]
	v_or_b32_e32 v44, v213, v215
	ds_read_b128 v[40:43], v44 offset:16384
	ds_read_b128 v[44:47], v44 offset:24576
	s_waitcnt lgkmcnt(0)
; #define AISSUE(k0, soff) do { const char* kb_ = (const char*)Kn + (size_t)(k0) * 4096; const char* rb_ = (const char*)Kr + (size_t)(k0) * 1024; \
;     char* st_ = lds + (soff) + tid * 16; \
;     GLDS(kb_ + vkn0, st_ + KOFF); GLDS(kb_ + vkn1, st_ + KOFF + 8192); GLDS(rb_ + vkr, st_ + KOFF + KROPE_OFF); \
;     GLDS(kb_ + vv0, st_); GLDS(kb_ + vv1, st_ + 8192); } while (0)
; #define WAITV(n) asm volatile("s_waitcnt vmcnt(" #n ")" ::: "memory")
; #define TBAR() do { __builtin_amdgcn_s_barrier(); SBAR(); } while (0)
; __device__ __forceinline__ void qkt(f32x16& p0, f32x16& p1, const char* Ks, const bf16x8* qr, int r32, int hi, float negM) {
; #pragma unroll
;   for (int r = 0; r < 16; ++r) { p0[r] = negM; p1[r] = negM; }
;   __builtin_amdgcn_s_setprio(1);
;   const char* kn = Ks + r32 * 256; const int xn = r32 & 15;
; #pragma unroll
;   for (int d0 = 0; d0 < 8; ++d0) { const int off = ((d0 * 2 + hi) ^ xn) << 4;
;     bf16x8 b0 = *reinterpret_cast<const bf16x8*>(kn + off);
;     bf16x8 b1 = *reinterpret_cast<const bf16x8*>(kn + 32 * 256 + off);
;     p0 = __builtin_amdgcn_mfma_f32_32x32x16_bf16(b0, qr[d0], p0, 0, 0, 0);
;     p1 = __builtin_amdgcn_mfma_f32_32x32x16_bf16(b1, qr[d0], p1, 0, 0, 0); }
;   const char* kr = Ks + KROPE_OFF + r32 * 128; const int xr = (r32 >> 1) & 7;
; #pragma unroll
;   for (int d0 = 8; d0 < 12; ++d0) { const int off = (((d0 - 8) * 2 + hi) ^ xr) << 4;
;     bf16x8 b0 = *reinterpret_cast<const bf16x8*>(kr + off);
;     bf16x8 b1 = *reinterpret_cast<const bf16x8*>(kr + 32 * 128 + off);
;     p0 = __builtin_amdgcn_mfma_f32_32x32x16_bf16(b0, qr[d0], p0, 0, 0, 0);
;     p1 = __builtin_amdgcn_mfma_f32_32x32x16_bf16(b1, qr[d0], p1, 0, 0, 0); }
;   __builtin_amdgcn_s_setprio(0);
; }
; __device__ __forceinline__ void attn_body(const u16* __restrict__ Qb, const u16* __restrict__ Kn, const u16* __restrict__ Kr,
;                                           u16* __restrict__ Ob, char* lds, int tid, const float* __restrict__ gq_, const float* __restrict__ tab_, int qpos0, float negM) {
;     ...
;   f32x16 pA0, pA1, pB0, pB1; bf16x8 pa0, pa1, pa2, pa3; constexpr int NT = SEQ / KVBLK;
;   WAITV(0); TBAR();
;   AISSUE(KVBLK, STG);
;   qkt(pA0, pA1, lds + KOFF, qr, r32, hi, negM); partialSM(pA0);
;   int prv = 0, cur = STG, nxt = 2 * STG;
	v_mfma_f32_32x32x16_bf16 v[16:31], v[40:43], v[132:135], v[16:31]
	v_bitop3_b32 v40, v207, v48, 4 bitop3:0x36
	v_lshlrev_b32_e32 v216, 4, v40
	v_mfma_f32_32x32x16_bf16 v[80:95], v[44:47], v[132:135], v[80:95]
	v_or_b32_e32 v44, v213, v216
	ds_read_b128 v[40:43], v44 offset:16384
	ds_read_b128 v[44:47], v44 offset:24576
	s_waitcnt lgkmcnt(0)
	v_mfma_f32_32x32x16_bf16 v[16:31], v[40:43], v[136:139], v[16:31]
	v_bitop3_b32 v40, v207, v48, 6 bitop3:0x36
	v_lshlrev_b32_e32 v217, 4, v40
	v_mfma_f32_32x32x16_bf16 v[80:95], v[44:47], v[136:139], v[80:95]
	v_or_b32_e32 v44, v213, v217
	ds_read_b128 v[40:43], v44 offset:16384
	ds_read_b128 v[44:47], v44 offset:24576
	s_waitcnt lgkmcnt(0)
	v_mfma_f32_32x32x16_bf16 v[16:31], v[40:43], v[140:143], v[16:31]
	v_bitop3_b32 v40, v207, v48, 8 bitop3:0x36
	v_lshlrev_b32_e32 v218, 4, v40
	v_mfma_f32_32x32x16_bf16 v[80:95], v[44:47], v[140:143], v[80:95]
	v_or_b32_e32 v44, v213, v218
	ds_read_b128 v[40:43], v44 offset:16384
	ds_read_b128 v[44:47], v44 offset:24576
	s_waitcnt lgkmcnt(0)
	v_mfma_f32_32x32x16_bf16 v[16:31], v[40:43], v[144:147], v[16:31]
	v_bitop3_b32 v40, v207, v48, 10 bitop3:0x36
	v_lshlrev_b32_e32 v219, 4, v40
	v_mfma_f32_32x32x16_bf16 v[80:95], v[44:47], v[144:147], v[80:95]
	v_or_b32_e32 v44, v213, v219
	ds_read_b128 v[40:43], v44 offset:16384
	ds_read_b128 v[44:47], v44 offset:24576
	s_waitcnt lgkmcnt(0)
	v_mfma_f32_32x32x16_bf16 v[16:31], v[40:43], v[148:151], v[16:31]
	v_bitop3_b32 v40, v207, v48, 12 bitop3:0x36
	v_lshlrev_b32_e32 v220, 4, v40
	v_mfma_f32_32x32x16_bf16 v[80:95], v[44:47], v[148:151], v[80:95]
	v_or_b32_e32 v44, v213, v220
	ds_read_b128 v[40:43], v44 offset:16384
	ds_read_b128 v[44:47], v44 offset:24576
	s_waitcnt lgkmcnt(0)
	v_mfma_f32_32x32x16_bf16 v[16:31], v[40:43], v[152:155], v[16:31]
	v_bitop3_b32 v40, v207, v48, 14 bitop3:0x36
	v_lshlrev_b32_e32 v221, 4, v40
	v_bfe_u32 v48, v96, 1, 3
	v_mfma_f32_32x32x16_bf16 v[80:95], v[44:47], v[152:155], v[80:95]
	v_or_b32_e32 v44, v213, v221
	ds_read_b128 v[40:43], v44 offset:16384
	ds_read_b128 v[44:47], v44 offset:24576
	s_waitcnt lgkmcnt(0)
	v_mfma_f32_32x32x16_bf16 v[16:31], v[40:43], v[156:159], v[16:31]
	v_lshrrev_b32_e32 v40, 1, v96
	v_bitop3_b32 v40, v207, v40, 7 bitop3:0x78
	v_lshlrev_b32_e32 v223, 4, v40
	v_mfma_f32_32x32x16_bf16 v[80:95], v[44:47], v[156:159], v[80:95]
	v_or_b32_e32 v44, v222, v223
	ds_read_b128 v[40:43], v44 offset:32768
	ds_read_b128 v[44:47], v44 offset:36864
	s_waitcnt lgkmcnt(0)
	v_mfma_f32_32x32x16_bf16 v[16:31], v[40:43], v[164:167], v[16:31]
	v_bitop3_b32 v40, v207, v48, 2 bitop3:0x36
	v_lshlrev_b32_e32 v224, 4, v40
	v_mfma_f32_32x32x16_bf16 v[80:95], v[44:47], v[164:167], v[80:95]
	v_or_b32_e32 v44, v222, v224
	ds_read_b128 v[40:43], v44 offset:32768
	ds_read_b128 v[44:47], v44 offset:36864
	s_waitcnt lgkmcnt(0)
	v_mfma_f32_32x32x16_bf16 v[16:31], v[40:43], v[172:175], v[16:31]
	v_bitop3_b32 v40, v207, v48, 4 bitop3:0x36
	v_lshlrev_b32_e32 v225, 4, v40
	v_mfma_f32_32x32x16_bf16 v[80:95], v[44:47], v[172:175], v[80:95]
	v_or_b32_e32 v44, v222, v225
	ds_read_b128 v[40:43], v44 offset:32768
	ds_read_b128 v[44:47], v44 offset:36864
	s_waitcnt lgkmcnt(0)
	v_mfma_f32_32x32x16_bf16 v[16:31], v[40:43], v[160:163], v[16:31]
	v_bitop3_b32 v40, v207, v48, 6 bitop3:0x36
	v_lshlrev_b32_e32 v226, 4, v40
	v_mfma_f32_32x32x16_bf16 v[80:95], v[44:47], v[160:163], v[80:95]
	v_or_b32_e32 v44, v222, v226
	ds_read_b128 v[40:43], v44 offset:32768
	ds_read_b128 v[44:47], v44 offset:36864
	s_waitcnt lgkmcnt(0)
	v_mfma_f32_32x32x16_bf16 v[16:31], v[40:43], v[168:171], v[16:31]
	v_mfma_f32_32x32x16_bf16 v[80:95], v[44:47], v[168:171], v[80:95]
	s_setprio 0
	s_nop 9
	v_exp_f32_e32 v240, v16
	v_exp_f32_e32 v242, v17
	v_exp_f32_e32 v238, v18
	v_exp_f32_e32 v241, v19
	v_exp_f32_e32 v236, v20
	v_exp_f32_e32 v239, v21
	v_exp_f32_e32 v235, v22
	v_exp_f32_e32 v237, v23
	v_exp_f32_e32 v232, v24
	v_exp_f32_e32 v234, v25
	v_exp_f32_e32 v230, v26
	v_exp_f32_e32 v233, v27
	v_exp_f32_e32 v228, v28
	v_exp_f32_e32 v231, v29
	v_exp_f32_e32 v227, v30
	v_exp_f32_e32 v229, v31
	s_or_b32 s48, s63, s80
	s_mov_b32 s49, s64
	v_lshl_add_u64 v[178:179], s[48:49], 0, v[34:35]
	s_or_b32 s48, s59, s79
	s_mov_b32 s49, s60
	v_lshl_add_u64 v[180:181], s[48:49], 0, v[38:39]
	v_lshl_add_u64 v[182:183], s[48:49], 0, v[36:37]
	v_lshl_add_u64 v[184:185], s[48:49], 0, v[176:177]
	v_lshl_add_u64 v[186:187], s[48:49], 0, v[32:33]
	s_mov_b32 s54, 0x14000
	s_mov_b32 s48, -1
	s_mov_b32 s49, 0xa000
	v_mov_b32_e32 v176, 0
	v_mov_b32_e32 v16, 0
	v_mov_b32_e32 v17, v177
	v_mov_b32_e32 v18, v177
	v_mov_b32_e32 v19, v177
	v_mov_b32_e32 v20, v177
	v_mov_b32_e32 v21, v177
	v_mov_b32_e32 v22, v177
	v_mov_b32_e32 v23, v177
	v_mov_b32_e32 v24, v177
	v_mov_b32_e32 v25, v177
	v_mov_b32_e32 v26, v177
	v_mov_b32_e32 v27, v177
	v_mov_b32_e32 v28, v177
	v_mov_b32_e32 v29, v177
	v_mov_b32_e32 v30, v177
	v_mov_b32_e32 v31, v177
	v_mov_b32_e32 v32, 0
	v_mov_b32_e32 v34, v177
	v_mov_b32_e32 v36, v177
	v_mov_b32_e32 v38, v177
	v_mov_b32_e32 v40, v177
	v_mov_b32_e32 v41, v177
	v_mov_b32_e32 v42, v177
	v_mov_b32_e32 v43, v177
	v_mov_b32_e32 v44, v177
	v_mov_b32_e32 v45, v177
	v_mov_b32_e32 v46, v177
	v_mov_b32_e32 v47, v177
	v_mov_b32_e32 v48, 0
	v_mov_b32_e32 v49, v177
	v_mov_b32_e32 v50, v177
	v_mov_b32_e32 v51, v177
	v_mov_b32_e32 v52, v177
	v_mov_b32_e32 v53, v177
	v_mov_b32_e32 v54, v177
	v_mov_b32_e32 v55, v177
	v_mov_b32_e32 v56, v177
	v_mov_b32_e32 v57, v177
	v_mov_b32_e32 v58, v177
	v_mov_b32_e32 v59, v177
	v_mov_b32_e32 v60, v177
	v_mov_b32_e32 v61, v177
	v_mov_b32_e32 v62, v177
	v_mov_b32_e32 v63, v177
	v_mov_b32_e32 v64, 0
	v_mov_b32_e32 v65, v177
	v_mov_b32_e32 v66, v177
	v_mov_b32_e32 v67, v177
	v_mov_b32_e32 v68, v177
	v_mov_b32_e32 v69, v177
	v_mov_b32_e32 v70, v177
	v_mov_b32_e32 v71, v177
	v_mov_b32_e32 v72, v177
	v_mov_b32_e32 v73, v177
	v_mov_b32_e32 v74, v177
	v_mov_b32_e32 v75, v177
	v_mov_b32_e32 v76, v177
	v_mov_b32_e32 v77, v177
	v_mov_b32_e32 v78, v177
	v_mov_b32_e32 v79, v177
